# gate arrays ga/gb stored with permuted in-band layout so P2 stores and P5 loads cover 512 contiguous bytes
# speedup vs baseline: 1.0077x; 1.0077x over previous
.LBB0_407:
	s_nop 15
	s_nop 15
	s_lshl_b32 s54, s86, 8
	s_cmp_gt_i32 s86, 6
	s_mov_b64 s[52:53], -1
	s_mov_b32 s96, s8
	s_cbranch_scc0 .LBB0_409
	s_add_i32 s48, s54, 0xfffff900
	s_lshl_b32 s48, s48, 4
	s_add_u32 s48, s63, s48
	s_addc_u32 s49, s64, 0
	s_mov_b64 s[52:53], 0
.LBB0_409:
	s_andn2_b64 vcc, exec, s[52:53]
	s_cbranch_vccnz .LBB0_411
	s_addk_i32 s54, 0xfd00
	s_ashr_i32 s49, s54, 31
	s_lshl_b32 s98, s54, 4
	s_add_u32 s48, s61, s98
	s_addc_u32 s49, s62, s49
.LBB0_411:
	v_mul_f32_e32 v5, 0xbfb8aa3b, v159
	v_exp_f32_e32 v5, v5
	v_mul_f32_e32 v6, 0xbfb8aa3b, v160
	v_exp_f32_e32 v7, v6
	v_mul_f32_e32 v6, 0xbfb8aa3b, v161
	v_exp_f32_e32 v9, v6
	v_add_f32_e32 v5, 1.0, v5
	v_rcp_f32_e32 v6, v5
	v_add_f32_e32 v5, 1.0, v7
	v_rcp_f32_e32 v8, v5
	v_add_f32_e32 v5, 1.0, v9
	v_mul_f32_e32 v7, 0xbfb8aa3b, v154
	v_mul_f32_e32 v9, 0xbfb8aa3b, v155
	v_exp_f32_e32 v7, v7
	v_exp_f32_e32 v9, v9
	v_mul_f32_e32 v4, 0xbfb8aa3b, v158
	v_exp_f32_e32 v4, v4
	v_rcp_f32_e32 v10, v5
	v_add_f32_e32 v5, 1.0, v7
	v_add_f32_e32 v7, 1.0, v9
	v_mul_f32_e32 v9, 0xbfb8aa3b, v156
	v_exp_f32_e32 v9, v9
	v_mul_f32_e32 v11, 0xbfb8aa3b, v157
	v_add_f32_e32 v4, 1.0, v4
	v_exp_f32_e32 v11, v11
	v_rcp_f32_e32 v4, v4
	v_rcp_f32_e32 v5, v5
	v_rcp_f32_e32 v7, v7
	v_add_f32_e32 v9, 1.0, v9
	v_rcp_f32_e32 v9, v9
	v_add_f32_e32 v11, 1.0, v11
	v_rcp_f32_e32 v11, v11
	v_pk_fma_f32 v[4:5], v[4:5], s[30:31], 0.5 op_sel_hi:[1,0,0]
	v_lshl_add_u32 v2, s46, 8, v179
	v_cvt_u32_f32_e32 v12, v5
	v_cvt_u32_f32_e32 v13, v4
	v_pk_fma_f32 v[4:5], v[6:7], s[30:31], 0.5 op_sel_hi:[1,0,0]
	v_ashrrev_i32_e32 v3, 31, v2
	v_cvt_u32_f32_e32 v6, v4
	v_cvt_u32_f32_e32 v7, v5
	v_pk_fma_f32 v[4:5], v[8:9], s[30:31], 0.5 op_sel_hi:[1,0,0]
	v_lshlrev_b64 v[2:3], 10, v[2:3]
	v_cvt_u32_f32_sdwa v8, v4 dst_sel:WORD_1 dst_unused:UNUSED_PAD src0_sel:DWORD
	v_cvt_u32_f32_sdwa v9, v5 dst_sel:WORD_1 dst_unused:UNUSED_PAD src0_sel:DWORD
	v_pk_fma_f32 v[4:5], v[10:11], s[30:31], 0.5 op_sel_hi:[1,0,0]
	v_lshlrev_b32_e32 v6, 8, v6
	v_cvt_u32_f32_sdwa v4, v4 dst_sel:BYTE_3 dst_unused:UNUSED_PAD src0_sel:DWORD
	v_cvt_u32_f32_sdwa v5, v5 dst_sel:BYTE_3 dst_unused:UNUSED_PAD src0_sel:DWORD
	v_lshlrev_b32_e32 v7, 8, v7
	v_or_b32_e32 v6, v6, v13
	v_or_b32_e32 v7, v7, v12
	v_or_b32_e32 v6, v6, v8
	v_or_b32_e32 v7, v7, v9
	v_or_b32_e32 v4, v6, v4
	v_mul_f32_e32 v6, 0xbfb8aa3b, v150
	v_or_b32_e32 v5, v7, v5
	v_exp_f32_e32 v6, v6
	v_mul_f32_e32 v7, 0xbfb8aa3b, v151
	v_exp_f32_e32 v7, v7
	v_add3_u32 v2, v2, s14, v162
	v_bfe_u32 v254, v2, 5, 5
	v_bfe_u32 v255, v2, 10, 4
	v_and_b32_e32 v2, 0xffffc01f, v2
	v_lshl_or_b32 v2, v254, 9, v2
	v_lshl_or_b32 v2, v255, 5, v2
	v_lshl_add_u64 v[2:3], s[48:49], 0, v[2:3]
	global_store_dwordx2 v[2:3], v[4:5], off
	v_add_f32_e32 v4, 1.0, v6
	v_mul_f32_e32 v6, 0xbfb8aa3b, v152
	v_add_f32_e32 v5, 1.0, v7
	v_exp_f32_e32 v7, v6
	v_mul_f32_e32 v6, 0xbfb8aa3b, v153
	v_exp_f32_e32 v9, v6
	v_rcp_f32_e32 v6, v5
	v_add_f32_e32 v5, 1.0, v7
	v_rcp_f32_e32 v8, v5
	v_add_f32_e32 v5, 1.0, v9
	v_mul_f32_e32 v7, 0xbfb8aa3b, v146
	v_mul_f32_e32 v9, 0xbfb8aa3b, v147
	v_exp_f32_e32 v7, v7
	v_exp_f32_e32 v9, v9
	v_rcp_f32_e32 v10, v5
	v_mul_f32_e32 v11, 0xbfb8aa3b, v149
	v_add_f32_e32 v5, 1.0, v7
	v_add_f32_e32 v7, 1.0, v9
	v_mul_f32_e32 v9, 0xbfb8aa3b, v148
	v_exp_f32_e32 v9, v9
	v_exp_f32_e32 v11, v11
	v_rcp_f32_e32 v4, v4
	v_rcp_f32_e32 v5, v5
	v_rcp_f32_e32 v7, v7
	v_add_f32_e32 v9, 1.0, v9
	v_rcp_f32_e32 v9, v9
	v_add_f32_e32 v11, 1.0, v11
	v_rcp_f32_e32 v11, v11
	v_pk_fma_f32 v[4:5], v[4:5], s[30:31], 0.5 op_sel_hi:[1,0,0]
	s_movk_i32 s46, 0x4000
	v_cvt_u32_f32_e32 v12, v5
	v_cvt_u32_f32_e32 v13, v4
	v_pk_fma_f32 v[4:5], v[6:7], s[30:31], 0.5 op_sel_hi:[1,0,0]
	s_nop 0
	v_cvt_u32_f32_e32 v6, v4
	v_cvt_u32_f32_e32 v7, v5
	v_pk_fma_f32 v[4:5], v[8:9], s[30:31], 0.5 op_sel_hi:[1,0,0]
	v_lshlrev_b32_e32 v6, 8, v6
	v_cvt_u32_f32_sdwa v8, v4 dst_sel:WORD_1 dst_unused:UNUSED_PAD src0_sel:DWORD
	v_cvt_u32_f32_sdwa v9, v5 dst_sel:WORD_1 dst_unused:UNUSED_PAD src0_sel:DWORD
	v_pk_fma_f32 v[4:5], v[10:11], s[30:31], 0.5 op_sel_hi:[1,0,0]
	v_lshlrev_b32_e32 v7, 8, v7
	v_cvt_u32_f32_sdwa v4, v4 dst_sel:BYTE_3 dst_unused:UNUSED_PAD src0_sel:DWORD
	v_cvt_u32_f32_sdwa v5, v5 dst_sel:BYTE_3 dst_unused:UNUSED_PAD src0_sel:DWORD
	v_or_b32_e32 v6, v6, v13
	v_or_b32_e32 v7, v7, v12
	v_or_b32_e32 v6, v6, v8
	v_or_b32_e32 v7, v7, v9
	v_or_b32_e32 v4, v6, v4
	v_mul_f32_e32 v6, 0xbfb8aa3b, v142
	v_or_b32_e32 v5, v7, v5
	v_exp_f32_e32 v6, v6
	v_mul_f32_e32 v7, 0xbfb8aa3b, v143
	v_exp_f32_e32 v7, v7
	global_store_dwordx2 v[2:3], v[4:5], off offset:2048
	v_add_f32_e32 v4, 1.0, v6
	v_mul_f32_e32 v6, 0xbfb8aa3b, v144
	v_add_f32_e32 v5, 1.0, v7
	v_exp_f32_e32 v7, v6
	v_mul_f32_e32 v6, 0xbfb8aa3b, v145
	v_exp_f32_e32 v9, v6
	v_rcp_f32_e32 v6, v5
	v_add_f32_e32 v5, 1.0, v7
	v_rcp_f32_e32 v8, v5
	v_add_f32_e32 v5, 1.0, v9
	v_mul_f32_e32 v7, 0xbfb8aa3b, v138
	v_mul_f32_e32 v9, 0xbfb8aa3b, v139
	v_exp_f32_e32 v7, v7
	v_exp_f32_e32 v9, v9
	v_rcp_f32_e32 v10, v5
	v_rcp_f32_e32 v4, v4
	v_add_f32_e32 v5, 1.0, v7
	v_add_f32_e32 v7, 1.0, v9
	v_mul_f32_e32 v9, 0xbfb8aa3b, v140
	v_exp_f32_e32 v9, v9
	v_rcp_f32_e32 v5, v5
	v_mul_f32_e32 v11, 0xbfb8aa3b, v141
	v_exp_f32_e32 v11, v11
	v_rcp_f32_e32 v7, v7
	v_add_f32_e32 v9, 1.0, v9
	v_rcp_f32_e32 v9, v9
	v_pk_fma_f32 v[4:5], v[4:5], s[30:31], 0.5 op_sel_hi:[1,0,0]
	v_add_f32_e32 v11, 1.0, v11
	v_cvt_u32_f32_e32 v12, v5
	v_cvt_u32_f32_e32 v13, v4
	v_pk_fma_f32 v[4:5], v[6:7], s[30:31], 0.5 op_sel_hi:[1,0,0]
	v_rcp_f32_e32 v11, v11
	v_cvt_u32_f32_e32 v6, v4
	v_cvt_u32_f32_e32 v7, v5
	v_pk_fma_f32 v[4:5], v[8:9], s[30:31], 0.5 op_sel_hi:[1,0,0]
	v_lshlrev_b32_e32 v6, 8, v6
	v_cvt_u32_f32_sdwa v8, v4 dst_sel:WORD_1 dst_unused:UNUSED_PAD src0_sel:DWORD
	v_cvt_u32_f32_sdwa v9, v5 dst_sel:WORD_1 dst_unused:UNUSED_PAD src0_sel:DWORD
	v_pk_fma_f32 v[4:5], v[10:11], s[30:31], 0.5 op_sel_hi:[1,0,0]
	v_lshlrev_b32_e32 v7, 8, v7
	v_cvt_u32_f32_sdwa v4, v4 dst_sel:BYTE_3 dst_unused:UNUSED_PAD src0_sel:DWORD
	v_or_b32_e32 v6, v6, v13
	v_cvt_u32_f32_sdwa v5, v5 dst_sel:BYTE_3 dst_unused:UNUSED_PAD src0_sel:DWORD
	v_or_b32_e32 v7, v7, v12
	v_or_b32_e32 v6, v6, v8
	v_mul_f32_e32 v8, 0xbfb8aa3b, v134
	v_or_b32_e32 v7, v7, v9
	v_exp_f32_e32 v8, v8
	v_mul_f32_e32 v9, 0xbfb8aa3b, v135
	v_exp_f32_e32 v9, v9
	v_or_b32_e32 v4, v6, v4
	v_add_co_u32_e32 v6, vcc, s46, v2
	v_or_b32_e32 v5, v7, v5
	s_nop 0
	v_addc_co_u32_e32 v7, vcc, 0, v3, vcc
	global_store_dwordx2 v[6:7], v[4:5], off
	v_add_f32_e32 v4, 1.0, v8
	v_mul_f32_e32 v8, 0xbfb8aa3b, v136
	v_add_f32_e32 v5, 1.0, v9
	v_exp_f32_e32 v9, v8
	v_mul_f32_e32 v8, 0xbfb8aa3b, v137
	v_exp_f32_e32 v11, v8
	v_rcp_f32_e32 v8, v5
	v_add_f32_e32 v5, 1.0, v9
	v_rcp_f32_e32 v10, v5
	v_add_f32_e32 v5, 1.0, v11
	v_mul_f32_e32 v9, 0xbfb8aa3b, v130
	v_mul_f32_e32 v11, 0xbfb8aa3b, v131
	v_exp_f32_e32 v9, v9
	v_exp_f32_e32 v11, v11
	v_rcp_f32_e32 v12, v5
	v_mul_f32_e32 v13, 0xbfb8aa3b, v133
	v_add_f32_e32 v5, 1.0, v9
	v_add_f32_e32 v9, 1.0, v11
	v_mul_f32_e32 v11, 0xbfb8aa3b, v132
	v_exp_f32_e32 v11, v11
	v_exp_f32_e32 v13, v13
	v_rcp_f32_e32 v4, v4
	v_rcp_f32_e32 v5, v5
	v_rcp_f32_e32 v9, v9
	v_add_f32_e32 v11, 1.0, v11
	v_rcp_f32_e32 v11, v11
	v_add_f32_e32 v13, 1.0, v13
	v_rcp_f32_e32 v13, v13
	v_pk_fma_f32 v[4:5], v[4:5], s[30:31], 0.5 op_sel_hi:[1,0,0]
	s_mov_b32 s46, 0x8000
	v_cvt_u32_f32_e32 v14, v5
	v_cvt_u32_f32_e32 v15, v4
	v_pk_fma_f32 v[4:5], v[8:9], s[30:31], 0.5 op_sel_hi:[1,0,0]
	s_nop 0
	v_cvt_u32_f32_e32 v9, v5
	v_cvt_u32_f32_e32 v8, v4
	v_pk_fma_f32 v[4:5], v[10:11], s[30:31], 0.5 op_sel_hi:[1,0,0]
	v_lshlrev_b32_e32 v9, 8, v9
	v_cvt_u32_f32_sdwa v10, v4 dst_sel:WORD_1 dst_unused:UNUSED_PAD src0_sel:DWORD
	v_cvt_u32_f32_sdwa v11, v5 dst_sel:WORD_1 dst_unused:UNUSED_PAD src0_sel:DWORD
	v_pk_fma_f32 v[4:5], v[12:13], s[30:31], 0.5 op_sel_hi:[1,0,0]
	v_or_b32_e32 v9, v9, v14
	v_cvt_u32_f32_sdwa v5, v5 dst_sel:BYTE_3 dst_unused:UNUSED_PAD src0_sel:DWORD
	v_cvt_u32_f32_sdwa v4, v4 dst_sel:BYTE_3 dst_unused:UNUSED_PAD src0_sel:DWORD
	v_lshlrev_b32_e32 v8, 8, v8
	v_or_b32_e32 v9, v9, v11
	v_or_b32_e32 v8, v8, v15
	v_or_b32_e32 v5, v9, v5
	v_mul_f32_e32 v9, 0xbfb8aa3b, v127
	v_or_b32_e32 v8, v8, v10
	v_exp_f32_e32 v9, v9
	v_or_b32_e32 v4, v8, v4
	global_store_dwordx2 v[6:7], v[4:5], off offset:2048
	v_mul_f32_e32 v6, 0xbfb8aa3b, v128
	v_mul_f32_e32 v8, 0xbfb8aa3b, v126
	v_exp_f32_e32 v7, v6
	v_mul_f32_e32 v6, 0xbfb8aa3b, v129
	v_exp_f32_e32 v8, v8
	v_add_f32_e32 v5, 1.0, v9
	v_exp_f32_e32 v9, v6
	v_rcp_f32_e32 v6, v5
	v_add_f32_e32 v5, 1.0, v7
	v_add_f32_e32 v4, 1.0, v8
	v_rcp_f32_e32 v8, v5
	v_add_f32_e32 v5, 1.0, v9
	v_mul_f32_e32 v7, 0xbfb8aa3b, v122
	v_mul_f32_e32 v9, 0xbfb8aa3b, v123
	v_exp_f32_e32 v7, v7
	v_exp_f32_e32 v9, v9
	v_rcp_f32_e32 v10, v5
	v_rcp_f32_e32 v4, v4
	v_add_f32_e32 v5, 1.0, v7
	v_add_f32_e32 v7, 1.0, v9
	v_mul_f32_e32 v9, 0xbfb8aa3b, v124
	v_exp_f32_e32 v9, v9
	v_rcp_f32_e32 v5, v5
	v_mul_f32_e32 v11, 0xbfb8aa3b, v125
	v_exp_f32_e32 v11, v11
	v_rcp_f32_e32 v7, v7
	v_add_f32_e32 v9, 1.0, v9
	v_rcp_f32_e32 v9, v9
	v_pk_fma_f32 v[4:5], v[4:5], s[30:31], 0.5 op_sel_hi:[1,0,0]
	v_add_f32_e32 v11, 1.0, v11
	v_cvt_u32_f32_e32 v12, v5
	v_cvt_u32_f32_e32 v13, v4
	v_pk_fma_f32 v[4:5], v[6:7], s[30:31], 0.5 op_sel_hi:[1,0,0]
	v_rcp_f32_e32 v11, v11
	v_cvt_u32_f32_e32 v6, v4
	v_cvt_u32_f32_e32 v7, v5
	v_pk_fma_f32 v[4:5], v[8:9], s[30:31], 0.5 op_sel_hi:[1,0,0]
	v_lshlrev_b32_e32 v6, 8, v6
	v_cvt_u32_f32_sdwa v8, v4 dst_sel:WORD_1 dst_unused:UNUSED_PAD src0_sel:DWORD
	v_cvt_u32_f32_sdwa v9, v5 dst_sel:WORD_1 dst_unused:UNUSED_PAD src0_sel:DWORD
	v_pk_fma_f32 v[4:5], v[10:11], s[30:31], 0.5 op_sel_hi:[1,0,0]
	v_lshlrev_b32_e32 v7, 8, v7
	v_cvt_u32_f32_sdwa v4, v4 dst_sel:BYTE_3 dst_unused:UNUSED_PAD src0_sel:DWORD
	v_or_b32_e32 v6, v6, v13
	v_cvt_u32_f32_sdwa v5, v5 dst_sel:BYTE_3 dst_unused:UNUSED_PAD src0_sel:DWORD
	v_or_b32_e32 v7, v7, v12
	v_or_b32_e32 v6, v6, v8
	v_mul_f32_e32 v8, 0xbfb8aa3b, v118
	v_or_b32_e32 v7, v7, v9
	v_exp_f32_e32 v8, v8
	v_mul_f32_e32 v9, 0xbfb8aa3b, v119
	v_exp_f32_e32 v9, v9
	v_or_b32_e32 v4, v6, v4
	v_add_co_u32_e32 v6, vcc, s46, v2
	v_or_b32_e32 v5, v7, v5
	s_nop 0
	v_addc_co_u32_e32 v7, vcc, 0, v3, vcc
	global_store_dwordx2 v[6:7], v[4:5], off
	v_add_f32_e32 v4, 1.0, v8
	v_mul_f32_e32 v8, 0xbfb8aa3b, v120
	v_add_f32_e32 v5, 1.0, v9
	v_exp_f32_e32 v9, v8
	v_mul_f32_e32 v8, 0xbfb8aa3b, v121
	v_exp_f32_e32 v11, v8
	v_rcp_f32_e32 v8, v5
	v_add_f32_e32 v5, 1.0, v9
	v_rcp_f32_e32 v10, v5
	v_add_f32_e32 v5, 1.0, v11
	v_mul_f32_e32 v9, 0xbfb8aa3b, v114
	v_mul_f32_e32 v11, 0xbfb8aa3b, v115
	v_exp_f32_e32 v9, v9
	v_exp_f32_e32 v11, v11
	v_rcp_f32_e32 v12, v5
	v_mul_f32_e32 v13, 0xbfb8aa3b, v117
	v_add_f32_e32 v5, 1.0, v9
	v_add_f32_e32 v9, 1.0, v11
	v_mul_f32_e32 v11, 0xbfb8aa3b, v116
	v_exp_f32_e32 v11, v11
	v_exp_f32_e32 v13, v13
	v_rcp_f32_e32 v4, v4
	v_rcp_f32_e32 v5, v5
	v_rcp_f32_e32 v9, v9
	v_add_f32_e32 v11, 1.0, v11
	v_rcp_f32_e32 v11, v11
	v_add_f32_e32 v13, 1.0, v13
	v_rcp_f32_e32 v13, v13
	v_pk_fma_f32 v[4:5], v[4:5], s[30:31], 0.5 op_sel_hi:[1,0,0]
	s_mov_b32 s46, 0xc000
	v_cvt_u32_f32_e32 v14, v5
	v_cvt_u32_f32_e32 v15, v4
	v_pk_fma_f32 v[4:5], v[8:9], s[30:31], 0.5 op_sel_hi:[1,0,0]
	s_nop 0
	v_cvt_u32_f32_e32 v9, v5
	v_cvt_u32_f32_e32 v8, v4
	v_pk_fma_f32 v[4:5], v[10:11], s[30:31], 0.5 op_sel_hi:[1,0,0]
	v_lshlrev_b32_e32 v9, 8, v9
	v_cvt_u32_f32_sdwa v10, v4 dst_sel:WORD_1 dst_unused:UNUSED_PAD src0_sel:DWORD
	v_cvt_u32_f32_sdwa v11, v5 dst_sel:WORD_1 dst_unused:UNUSED_PAD src0_sel:DWORD
	v_pk_fma_f32 v[4:5], v[12:13], s[30:31], 0.5 op_sel_hi:[1,0,0]
	v_or_b32_e32 v9, v9, v14
	v_cvt_u32_f32_sdwa v5, v5 dst_sel:BYTE_3 dst_unused:UNUSED_PAD src0_sel:DWORD
	v_cvt_u32_f32_sdwa v4, v4 dst_sel:BYTE_3 dst_unused:UNUSED_PAD src0_sel:DWORD
	v_lshlrev_b32_e32 v8, 8, v8
	v_or_b32_e32 v9, v9, v11
	v_or_b32_e32 v8, v8, v15
	v_or_b32_e32 v5, v9, v5
	v_mul_f32_e32 v9, 0xbfb8aa3b, v111
	v_or_b32_e32 v8, v8, v10
	v_exp_f32_e32 v9, v9
	v_or_b32_e32 v4, v8, v4
	global_store_dwordx2 v[6:7], v[4:5], off offset:2048
	v_mul_f32_e32 v6, 0xbfb8aa3b, v112
	v_mul_f32_e32 v8, 0xbfb8aa3b, v110
	v_exp_f32_e32 v7, v6
	v_mul_f32_e32 v6, 0xbfb8aa3b, v113
	v_exp_f32_e32 v8, v8
	v_add_f32_e32 v5, 1.0, v9
	v_exp_f32_e32 v9, v6
	v_rcp_f32_e32 v6, v5
	v_add_f32_e32 v5, 1.0, v7
	v_add_f32_e32 v4, 1.0, v8
	v_rcp_f32_e32 v8, v5
	v_add_f32_e32 v5, 1.0, v9
	v_mul_f32_e32 v7, 0xbfb8aa3b, v106
	v_mul_f32_e32 v9, 0xbfb8aa3b, v107
	v_exp_f32_e32 v7, v7
	v_exp_f32_e32 v9, v9
	v_rcp_f32_e32 v10, v5
	v_rcp_f32_e32 v4, v4
	v_add_f32_e32 v5, 1.0, v7
	v_add_f32_e32 v7, 1.0, v9
	v_mul_f32_e32 v9, 0xbfb8aa3b, v108
	v_exp_f32_e32 v9, v9
	v_rcp_f32_e32 v5, v5
	v_mul_f32_e32 v11, 0xbfb8aa3b, v109
	v_exp_f32_e32 v11, v11
	v_rcp_f32_e32 v7, v7
	v_add_f32_e32 v9, 1.0, v9
	v_rcp_f32_e32 v9, v9
	v_pk_fma_f32 v[4:5], v[4:5], s[30:31], 0.5 op_sel_hi:[1,0,0]
	v_add_f32_e32 v11, 1.0, v11
	v_cvt_u32_f32_e32 v12, v5
	v_cvt_u32_f32_e32 v13, v4
	v_pk_fma_f32 v[4:5], v[6:7], s[30:31], 0.5 op_sel_hi:[1,0,0]
	v_rcp_f32_e32 v11, v11
	v_cvt_u32_f32_e32 v6, v4
	v_cvt_u32_f32_e32 v7, v5
	v_pk_fma_f32 v[4:5], v[8:9], s[30:31], 0.5 op_sel_hi:[1,0,0]
	v_lshlrev_b32_e32 v6, 8, v6
	v_cvt_u32_f32_sdwa v8, v4 dst_sel:WORD_1 dst_unused:UNUSED_PAD src0_sel:DWORD
	v_cvt_u32_f32_sdwa v9, v5 dst_sel:WORD_1 dst_unused:UNUSED_PAD src0_sel:DWORD
	v_pk_fma_f32 v[4:5], v[10:11], s[30:31], 0.5 op_sel_hi:[1,0,0]
	v_lshlrev_b32_e32 v7, 8, v7
	v_cvt_u32_f32_sdwa v4, v4 dst_sel:BYTE_3 dst_unused:UNUSED_PAD src0_sel:DWORD
	v_or_b32_e32 v6, v6, v13
	v_cvt_u32_f32_sdwa v5, v5 dst_sel:BYTE_3 dst_unused:UNUSED_PAD src0_sel:DWORD
	v_or_b32_e32 v7, v7, v12
	v_or_b32_e32 v6, v6, v8
	v_mul_f32_e32 v8, 0xbfb8aa3b, v102
	v_or_b32_e32 v7, v7, v9
	v_exp_f32_e32 v8, v8
	v_mul_f32_e32 v9, 0xbfb8aa3b, v103
	v_exp_f32_e32 v9, v9
	v_or_b32_e32 v4, v6, v4
	v_add_co_u32_e32 v6, vcc, s46, v2
	v_or_b32_e32 v5, v7, v5
	s_nop 0
	v_addc_co_u32_e32 v7, vcc, 0, v3, vcc
	global_store_dwordx2 v[6:7], v[4:5], off
	v_add_f32_e32 v4, 1.0, v8
	v_mul_f32_e32 v8, 0xbfb8aa3b, v104
	v_add_f32_e32 v5, 1.0, v9
	v_exp_f32_e32 v9, v8
	v_mul_f32_e32 v8, 0xbfb8aa3b, v105
	v_exp_f32_e32 v11, v8
	v_rcp_f32_e32 v8, v5
	v_add_f32_e32 v5, 1.0, v9
	v_rcp_f32_e32 v10, v5
	v_add_f32_e32 v5, 1.0, v11
	v_mul_f32_e32 v9, 0xbfb8aa3b, v98
	v_mul_f32_e32 v11, 0xbfb8aa3b, v99
	v_exp_f32_e32 v9, v9
	v_exp_f32_e32 v11, v11
	v_rcp_f32_e32 v12, v5
	v_mul_f32_e32 v13, 0xbfb8aa3b, v101
	v_add_f32_e32 v5, 1.0, v9
	v_add_f32_e32 v9, 1.0, v11
	v_mul_f32_e32 v11, 0xbfb8aa3b, v100
	v_exp_f32_e32 v11, v11
	v_exp_f32_e32 v13, v13
	v_rcp_f32_e32 v4, v4
	v_rcp_f32_e32 v5, v5
	v_rcp_f32_e32 v9, v9
	v_add_f32_e32 v11, 1.0, v11
	v_rcp_f32_e32 v11, v11
	v_add_f32_e32 v13, 1.0, v13
	v_rcp_f32_e32 v13, v13
	v_pk_fma_f32 v[4:5], v[4:5], s[30:31], 0.5 op_sel_hi:[1,0,0]
	s_mov_b32 s46, 0x20000
	v_cvt_u32_f32_e32 v14, v5
	v_cvt_u32_f32_e32 v15, v4
	v_pk_fma_f32 v[4:5], v[8:9], s[30:31], 0.5 op_sel_hi:[1,0,0]
	s_nop 0
	v_cvt_u32_f32_e32 v9, v5
	v_cvt_u32_f32_e32 v8, v4
	v_pk_fma_f32 v[4:5], v[10:11], s[30:31], 0.5 op_sel_hi:[1,0,0]
	v_lshlrev_b32_e32 v9, 8, v9
	v_cvt_u32_f32_sdwa v10, v4 dst_sel:WORD_1 dst_unused:UNUSED_PAD src0_sel:DWORD
	v_cvt_u32_f32_sdwa v11, v5 dst_sel:WORD_1 dst_unused:UNUSED_PAD src0_sel:DWORD
	v_pk_fma_f32 v[4:5], v[12:13], s[30:31], 0.5 op_sel_hi:[1,0,0]
	v_or_b32_e32 v9, v9, v14
	v_cvt_u32_f32_sdwa v5, v5 dst_sel:BYTE_3 dst_unused:UNUSED_PAD src0_sel:DWORD
	v_cvt_u32_f32_sdwa v4, v4 dst_sel:BYTE_3 dst_unused:UNUSED_PAD src0_sel:DWORD
	v_lshlrev_b32_e32 v8, 8, v8
	v_or_b32_e32 v9, v9, v11
	v_or_b32_e32 v8, v8, v15
	v_or_b32_e32 v5, v9, v5
	v_mul_f32_e32 v9, 0xbfb8aa3b, v95
	v_or_b32_e32 v8, v8, v10
	v_exp_f32_e32 v9, v9
	v_or_b32_e32 v4, v8, v4
	global_store_dwordx2 v[6:7], v[4:5], off offset:2048
	v_mul_f32_e32 v6, 0xbfb8aa3b, v96
	v_mul_f32_e32 v8, 0xbfb8aa3b, v94
	v_exp_f32_e32 v7, v6
	v_mul_f32_e32 v6, 0xbfb8aa3b, v97
	v_exp_f32_e32 v8, v8
	v_add_f32_e32 v5, 1.0, v9
	v_exp_f32_e32 v9, v6
	v_rcp_f32_e32 v6, v5
	v_add_f32_e32 v5, 1.0, v7
	v_add_f32_e32 v4, 1.0, v8
	v_rcp_f32_e32 v8, v5
	v_add_f32_e32 v5, 1.0, v9
	v_mul_f32_e32 v7, 0xbfb8aa3b, v90
	v_mul_f32_e32 v9, 0xbfb8aa3b, v91
	v_exp_f32_e32 v7, v7
	v_exp_f32_e32 v9, v9
	v_rcp_f32_e32 v10, v5
	v_rcp_f32_e32 v4, v4
	v_add_f32_e32 v5, 1.0, v7
	v_add_f32_e32 v7, 1.0, v9
	v_mul_f32_e32 v9, 0xbfb8aa3b, v92
	v_exp_f32_e32 v9, v9
	v_rcp_f32_e32 v5, v5
	v_mul_f32_e32 v11, 0xbfb8aa3b, v93
	v_exp_f32_e32 v11, v11
	v_rcp_f32_e32 v7, v7
	v_add_f32_e32 v9, 1.0, v9
	v_rcp_f32_e32 v9, v9
	v_pk_fma_f32 v[4:5], v[4:5], s[30:31], 0.5 op_sel_hi:[1,0,0]
	v_add_f32_e32 v11, 1.0, v11
	v_cvt_u32_f32_e32 v12, v5
	v_cvt_u32_f32_e32 v13, v4
	v_pk_fma_f32 v[4:5], v[6:7], s[30:31], 0.5 op_sel_hi:[1,0,0]
	v_rcp_f32_e32 v11, v11
	v_cvt_u32_f32_e32 v6, v4
	v_cvt_u32_f32_e32 v7, v5
	v_pk_fma_f32 v[4:5], v[8:9], s[30:31], 0.5 op_sel_hi:[1,0,0]
	v_lshlrev_b32_e32 v6, 8, v6
	v_cvt_u32_f32_sdwa v8, v4 dst_sel:WORD_1 dst_unused:UNUSED_PAD src0_sel:DWORD
	v_cvt_u32_f32_sdwa v9, v5 dst_sel:WORD_1 dst_unused:UNUSED_PAD src0_sel:DWORD
	v_pk_fma_f32 v[4:5], v[10:11], s[30:31], 0.5 op_sel_hi:[1,0,0]
	v_lshlrev_b32_e32 v7, 8, v7
	v_cvt_u32_f32_sdwa v4, v4 dst_sel:BYTE_3 dst_unused:UNUSED_PAD src0_sel:DWORD
	v_or_b32_e32 v6, v6, v13
	v_cvt_u32_f32_sdwa v5, v5 dst_sel:BYTE_3 dst_unused:UNUSED_PAD src0_sel:DWORD
	v_or_b32_e32 v7, v7, v12
	v_or_b32_e32 v6, v6, v8
	v_mul_f32_e32 v8, 0xbfb8aa3b, v86
	v_or_b32_e32 v7, v7, v9
	v_exp_f32_e32 v8, v8
	v_mul_f32_e32 v9, 0xbfb8aa3b, v87
	v_exp_f32_e32 v9, v9
	v_or_b32_e32 v4, v6, v4
	v_add_co_u32_e32 v6, vcc, s46, v2
	v_or_b32_e32 v5, v7, v5
	s_nop 0
	v_addc_co_u32_e32 v7, vcc, 0, v3, vcc
	global_store_dwordx2 v[6:7], v[4:5], off
	v_add_f32_e32 v4, 1.0, v8
	v_mul_f32_e32 v8, 0xbfb8aa3b, v88
	v_add_f32_e32 v5, 1.0, v9
	v_exp_f32_e32 v9, v8
	v_mul_f32_e32 v8, 0xbfb8aa3b, v89
	v_exp_f32_e32 v11, v8
	v_rcp_f32_e32 v8, v5
	v_add_f32_e32 v5, 1.0, v9
	v_rcp_f32_e32 v10, v5
	v_add_f32_e32 v5, 1.0, v11
	v_mul_f32_e32 v9, 0xbfb8aa3b, v82
	v_mul_f32_e32 v11, 0xbfb8aa3b, v83
	v_exp_f32_e32 v9, v9
	v_exp_f32_e32 v11, v11
	v_rcp_f32_e32 v12, v5
	v_mul_f32_e32 v13, 0xbfb8aa3b, v85
	v_add_f32_e32 v5, 1.0, v9
	v_add_f32_e32 v9, 1.0, v11
	v_mul_f32_e32 v11, 0xbfb8aa3b, v84
	v_exp_f32_e32 v11, v11
	v_exp_f32_e32 v13, v13
	v_rcp_f32_e32 v4, v4
	v_rcp_f32_e32 v5, v5
	v_rcp_f32_e32 v9, v9
	v_add_f32_e32 v11, 1.0, v11
	v_rcp_f32_e32 v11, v11
	v_add_f32_e32 v13, 1.0, v13
	v_rcp_f32_e32 v13, v13
	v_pk_fma_f32 v[4:5], v[4:5], s[30:31], 0.5 op_sel_hi:[1,0,0]
	s_mov_b32 s46, 0x24000
	v_cvt_u32_f32_e32 v14, v5
	v_cvt_u32_f32_e32 v15, v4
	v_pk_fma_f32 v[4:5], v[8:9], s[30:31], 0.5 op_sel_hi:[1,0,0]
	s_nop 0
	v_cvt_u32_f32_e32 v9, v5
	v_cvt_u32_f32_e32 v8, v4
	v_pk_fma_f32 v[4:5], v[10:11], s[30:31], 0.5 op_sel_hi:[1,0,0]
	v_lshlrev_b32_e32 v9, 8, v9
	v_cvt_u32_f32_sdwa v10, v4 dst_sel:WORD_1 dst_unused:UNUSED_PAD src0_sel:DWORD
	v_cvt_u32_f32_sdwa v11, v5 dst_sel:WORD_1 dst_unused:UNUSED_PAD src0_sel:DWORD
	v_pk_fma_f32 v[4:5], v[12:13], s[30:31], 0.5 op_sel_hi:[1,0,0]
	v_or_b32_e32 v9, v9, v14
	v_cvt_u32_f32_sdwa v5, v5 dst_sel:BYTE_3 dst_unused:UNUSED_PAD src0_sel:DWORD
	v_cvt_u32_f32_sdwa v4, v4 dst_sel:BYTE_3 dst_unused:UNUSED_PAD src0_sel:DWORD
	v_lshlrev_b32_e32 v8, 8, v8
	v_or_b32_e32 v9, v9, v11
	v_or_b32_e32 v8, v8, v15
	v_or_b32_e32 v5, v9, v5
	v_mul_f32_e32 v9, 0xbfb8aa3b, v79
	v_or_b32_e32 v8, v8, v10
	v_exp_f32_e32 v9, v9
	v_or_b32_e32 v4, v8, v4
	global_store_dwordx2 v[6:7], v[4:5], off offset:2048
	v_mul_f32_e32 v6, 0xbfb8aa3b, v80
	v_mul_f32_e32 v8, 0xbfb8aa3b, v78
	v_exp_f32_e32 v7, v6
	v_mul_f32_e32 v6, 0xbfb8aa3b, v81
	v_exp_f32_e32 v8, v8
	v_add_f32_e32 v5, 1.0, v9
	v_exp_f32_e32 v9, v6
	v_rcp_f32_e32 v6, v5
	v_add_f32_e32 v5, 1.0, v7
	v_add_f32_e32 v4, 1.0, v8
	v_rcp_f32_e32 v8, v5
	v_add_f32_e32 v5, 1.0, v9
	v_mul_f32_e32 v7, 0xbfb8aa3b, v74
	v_mul_f32_e32 v9, 0xbfb8aa3b, v75
	v_exp_f32_e32 v7, v7
	v_exp_f32_e32 v9, v9
	v_rcp_f32_e32 v10, v5
	v_rcp_f32_e32 v4, v4
	v_add_f32_e32 v5, 1.0, v7
	v_add_f32_e32 v7, 1.0, v9
	v_mul_f32_e32 v9, 0xbfb8aa3b, v76
	v_exp_f32_e32 v9, v9
	v_rcp_f32_e32 v5, v5
	v_mul_f32_e32 v11, 0xbfb8aa3b, v77
	v_exp_f32_e32 v11, v11
	v_rcp_f32_e32 v7, v7
	v_add_f32_e32 v9, 1.0, v9
	v_rcp_f32_e32 v9, v9
	v_pk_fma_f32 v[4:5], v[4:5], s[30:31], 0.5 op_sel_hi:[1,0,0]
	v_add_f32_e32 v11, 1.0, v11
	v_cvt_u32_f32_e32 v12, v5
	v_cvt_u32_f32_e32 v13, v4
	v_pk_fma_f32 v[4:5], v[6:7], s[30:31], 0.5 op_sel_hi:[1,0,0]
	v_rcp_f32_e32 v11, v11
	v_cvt_u32_f32_e32 v6, v4
	v_cvt_u32_f32_e32 v7, v5
	v_pk_fma_f32 v[4:5], v[8:9], s[30:31], 0.5 op_sel_hi:[1,0,0]
	v_lshlrev_b32_e32 v6, 8, v6
	v_cvt_u32_f32_sdwa v8, v4 dst_sel:WORD_1 dst_unused:UNUSED_PAD src0_sel:DWORD
	v_cvt_u32_f32_sdwa v9, v5 dst_sel:WORD_1 dst_unused:UNUSED_PAD src0_sel:DWORD
	v_pk_fma_f32 v[4:5], v[10:11], s[30:31], 0.5 op_sel_hi:[1,0,0]
	v_lshlrev_b32_e32 v7, 8, v7
	v_cvt_u32_f32_sdwa v4, v4 dst_sel:BYTE_3 dst_unused:UNUSED_PAD src0_sel:DWORD
	v_or_b32_e32 v6, v6, v13
	v_cvt_u32_f32_sdwa v5, v5 dst_sel:BYTE_3 dst_unused:UNUSED_PAD src0_sel:DWORD
	v_or_b32_e32 v7, v7, v12
	v_or_b32_e32 v6, v6, v8
	v_mul_f32_e32 v8, 0xbfb8aa3b, v70
	v_or_b32_e32 v7, v7, v9
	v_exp_f32_e32 v8, v8
	v_mul_f32_e32 v9, 0xbfb8aa3b, v71
	v_exp_f32_e32 v9, v9
	v_or_b32_e32 v4, v6, v4
	v_add_co_u32_e32 v6, vcc, s46, v2
	v_or_b32_e32 v5, v7, v5
	s_nop 0
	v_addc_co_u32_e32 v7, vcc, 0, v3, vcc
	global_store_dwordx2 v[6:7], v[4:5], off
	v_add_f32_e32 v4, 1.0, v8
	v_mul_f32_e32 v8, 0xbfb8aa3b, v72
	v_add_f32_e32 v5, 1.0, v9
	v_exp_f32_e32 v9, v8
	v_mul_f32_e32 v8, 0xbfb8aa3b, v73
	v_exp_f32_e32 v11, v8
	v_rcp_f32_e32 v8, v5
	v_add_f32_e32 v5, 1.0, v9
	v_rcp_f32_e32 v10, v5
	v_add_f32_e32 v5, 1.0, v11
	v_mul_f32_e32 v9, 0xbfb8aa3b, v66
	v_mul_f32_e32 v11, 0xbfb8aa3b, v67
	v_exp_f32_e32 v9, v9
	v_exp_f32_e32 v11, v11
	v_rcp_f32_e32 v12, v5
	v_mul_f32_e32 v13, 0xbfb8aa3b, v69
	v_add_f32_e32 v5, 1.0, v9
	v_add_f32_e32 v9, 1.0, v11
	v_mul_f32_e32 v11, 0xbfb8aa3b, v68
	v_exp_f32_e32 v11, v11
	v_exp_f32_e32 v13, v13
	v_rcp_f32_e32 v4, v4
	v_rcp_f32_e32 v5, v5
	v_rcp_f32_e32 v9, v9
	v_add_f32_e32 v11, 1.0, v11
	v_rcp_f32_e32 v11, v11
	v_add_f32_e32 v13, 1.0, v13
	v_rcp_f32_e32 v13, v13
	v_pk_fma_f32 v[4:5], v[4:5], s[30:31], 0.5 op_sel_hi:[1,0,0]
	s_mov_b32 s46, 0x28000
	v_cvt_u32_f32_e32 v14, v5
	v_cvt_u32_f32_e32 v15, v4
	v_pk_fma_f32 v[4:5], v[8:9], s[30:31], 0.5 op_sel_hi:[1,0,0]
	s_nop 0
	v_cvt_u32_f32_e32 v9, v5
	v_cvt_u32_f32_e32 v8, v4
	v_pk_fma_f32 v[4:5], v[10:11], s[30:31], 0.5 op_sel_hi:[1,0,0]
	v_lshlrev_b32_e32 v9, 8, v9
	v_cvt_u32_f32_sdwa v10, v4 dst_sel:WORD_1 dst_unused:UNUSED_PAD src0_sel:DWORD
	v_cvt_u32_f32_sdwa v11, v5 dst_sel:WORD_1 dst_unused:UNUSED_PAD src0_sel:DWORD
	v_pk_fma_f32 v[4:5], v[12:13], s[30:31], 0.5 op_sel_hi:[1,0,0]
	v_or_b32_e32 v9, v9, v14
	v_cvt_u32_f32_sdwa v5, v5 dst_sel:BYTE_3 dst_unused:UNUSED_PAD src0_sel:DWORD
	v_cvt_u32_f32_sdwa v4, v4 dst_sel:BYTE_3 dst_unused:UNUSED_PAD src0_sel:DWORD
	v_lshlrev_b32_e32 v8, 8, v8
	v_or_b32_e32 v9, v9, v11
	v_or_b32_e32 v8, v8, v15
	v_or_b32_e32 v5, v9, v5
	v_mul_f32_e32 v9, 0xbfb8aa3b, v63
	v_or_b32_e32 v8, v8, v10
	v_exp_f32_e32 v9, v9
	v_or_b32_e32 v4, v8, v4
	global_store_dwordx2 v[6:7], v[4:5], off offset:2048
	v_mul_f32_e32 v6, 0xbfb8aa3b, v64
	v_mul_f32_e32 v8, 0xbfb8aa3b, v62
	v_exp_f32_e32 v7, v6
	v_mul_f32_e32 v6, 0xbfb8aa3b, v65
	v_exp_f32_e32 v8, v8
	v_add_f32_e32 v5, 1.0, v9
	v_exp_f32_e32 v9, v6
	v_rcp_f32_e32 v6, v5
	v_add_f32_e32 v5, 1.0, v7
	v_add_f32_e32 v4, 1.0, v8
	v_rcp_f32_e32 v8, v5
	v_add_f32_e32 v5, 1.0, v9
	v_mul_f32_e32 v7, 0xbfb8aa3b, v58
	v_mul_f32_e32 v9, 0xbfb8aa3b, v59
	v_exp_f32_e32 v7, v7
	v_exp_f32_e32 v9, v9
	v_rcp_f32_e32 v10, v5
	v_rcp_f32_e32 v4, v4
	v_add_f32_e32 v5, 1.0, v7
	v_add_f32_e32 v7, 1.0, v9
	v_mul_f32_e32 v9, 0xbfb8aa3b, v60
	v_exp_f32_e32 v9, v9
	v_rcp_f32_e32 v5, v5
	v_mul_f32_e32 v11, 0xbfb8aa3b, v61
	v_exp_f32_e32 v11, v11
	v_rcp_f32_e32 v7, v7
	v_add_f32_e32 v9, 1.0, v9
	v_rcp_f32_e32 v9, v9
	v_pk_fma_f32 v[4:5], v[4:5], s[30:31], 0.5 op_sel_hi:[1,0,0]
	v_add_f32_e32 v11, 1.0, v11
	v_cvt_u32_f32_e32 v12, v5
	v_cvt_u32_f32_e32 v13, v4
	v_pk_fma_f32 v[4:5], v[6:7], s[30:31], 0.5 op_sel_hi:[1,0,0]
	v_rcp_f32_e32 v11, v11
	v_cvt_u32_f32_e32 v6, v4
	v_cvt_u32_f32_e32 v7, v5
	v_pk_fma_f32 v[4:5], v[8:9], s[30:31], 0.5 op_sel_hi:[1,0,0]
	v_lshlrev_b32_e32 v6, 8, v6
	v_cvt_u32_f32_sdwa v8, v4 dst_sel:WORD_1 dst_unused:UNUSED_PAD src0_sel:DWORD
	v_cvt_u32_f32_sdwa v9, v5 dst_sel:WORD_1 dst_unused:UNUSED_PAD src0_sel:DWORD
	v_pk_fma_f32 v[4:5], v[10:11], s[30:31], 0.5 op_sel_hi:[1,0,0]
	v_lshlrev_b32_e32 v7, 8, v7
	v_cvt_u32_f32_sdwa v4, v4 dst_sel:BYTE_3 dst_unused:UNUSED_PAD src0_sel:DWORD
	v_or_b32_e32 v6, v6, v13
	v_cvt_u32_f32_sdwa v5, v5 dst_sel:BYTE_3 dst_unused:UNUSED_PAD src0_sel:DWORD
	v_or_b32_e32 v7, v7, v12
	v_or_b32_e32 v6, v6, v8
	v_mul_f32_e32 v8, 0xbfb8aa3b, v54
	v_or_b32_e32 v7, v7, v9
	v_exp_f32_e32 v8, v8
	v_mul_f32_e32 v9, 0xbfb8aa3b, v55
	v_exp_f32_e32 v9, v9
	v_or_b32_e32 v4, v6, v4
	v_add_co_u32_e32 v6, vcc, s46, v2
	v_or_b32_e32 v5, v7, v5
	s_nop 0
	v_addc_co_u32_e32 v7, vcc, 0, v3, vcc
	global_store_dwordx2 v[6:7], v[4:5], off
	v_add_f32_e32 v4, 1.0, v8
	v_mul_f32_e32 v8, 0xbfb8aa3b, v56
	v_add_f32_e32 v5, 1.0, v9
	v_exp_f32_e32 v9, v8
	v_mul_f32_e32 v8, 0xbfb8aa3b, v57
	v_exp_f32_e32 v11, v8
	v_rcp_f32_e32 v8, v5
	v_add_f32_e32 v5, 1.0, v9
	v_rcp_f32_e32 v10, v5
	v_add_f32_e32 v5, 1.0, v11
	v_mul_f32_e32 v9, 0xbfb8aa3b, v50
	v_mul_f32_e32 v11, 0xbfb8aa3b, v51
	v_exp_f32_e32 v9, v9
	v_exp_f32_e32 v11, v11
	v_rcp_f32_e32 v12, v5
	v_mul_f32_e32 v13, 0xbfb8aa3b, v53
	v_add_f32_e32 v5, 1.0, v9
	v_add_f32_e32 v9, 1.0, v11
	v_mul_f32_e32 v11, 0xbfb8aa3b, v52
	v_exp_f32_e32 v11, v11
	v_exp_f32_e32 v13, v13
	v_rcp_f32_e32 v4, v4
	v_rcp_f32_e32 v5, v5
	v_rcp_f32_e32 v9, v9
	v_add_f32_e32 v11, 1.0, v11
	v_rcp_f32_e32 v11, v11
	v_add_f32_e32 v13, 1.0, v13
	v_rcp_f32_e32 v13, v13
	v_pk_fma_f32 v[4:5], v[4:5], s[30:31], 0.5 op_sel_hi:[1,0,0]
	s_mov_b32 s46, 0x2c000
	v_cvt_u32_f32_e32 v14, v5
	v_cvt_u32_f32_e32 v15, v4
	v_pk_fma_f32 v[4:5], v[8:9], s[30:31], 0.5 op_sel_hi:[1,0,0]
	v_add_co_u32_e32 v2, vcc, s46, v2
	v_cvt_u32_f32_e32 v9, v5
	v_cvt_u32_f32_e32 v8, v4
	v_pk_fma_f32 v[4:5], v[10:11], s[30:31], 0.5 op_sel_hi:[1,0,0]
	v_addc_co_u32_e32 v3, vcc, 0, v3, vcc
	v_cvt_u32_f32_sdwa v10, v4 dst_sel:WORD_1 dst_unused:UNUSED_PAD src0_sel:DWORD
	v_cvt_u32_f32_sdwa v11, v5 dst_sel:WORD_1 dst_unused:UNUSED_PAD src0_sel:DWORD
	v_pk_fma_f32 v[4:5], v[12:13], s[30:31], 0.5 op_sel_hi:[1,0,0]
	v_lshlrev_b32_e32 v9, 8, v9
	v_cvt_u32_f32_sdwa v5, v5 dst_sel:BYTE_3 dst_unused:UNUSED_PAD src0_sel:DWORD
	v_cvt_u32_f32_sdwa v4, v4 dst_sel:BYTE_3 dst_unused:UNUSED_PAD src0_sel:DWORD
	v_or_b32_e32 v9, v9, v14
	v_lshlrev_b32_e32 v8, 8, v8
	v_or_b32_e32 v9, v9, v11
	v_or_b32_e32 v8, v8, v15
	v_or_b32_e32 v5, v9, v5
	v_mul_f32_e32 v9, 0xbfb8aa3b, v47
	v_or_b32_e32 v8, v8, v10
	v_exp_f32_e32 v9, v9
	v_or_b32_e32 v4, v8, v4
	global_store_dwordx2 v[6:7], v[4:5], off offset:2048
	v_mul_f32_e32 v6, 0xbfb8aa3b, v48
	v_mul_f32_e32 v8, 0xbfb8aa3b, v46
	v_exp_f32_e32 v7, v6
	v_mul_f32_e32 v6, 0xbfb8aa3b, v49
	v_exp_f32_e32 v8, v8
	v_add_f32_e32 v5, 1.0, v9
	v_exp_f32_e32 v9, v6
	v_rcp_f32_e32 v6, v5
	v_add_f32_e32 v5, 1.0, v7
	v_add_f32_e32 v4, 1.0, v8
	v_rcp_f32_e32 v8, v5
	v_add_f32_e32 v5, 1.0, v9
	v_mul_f32_e32 v7, 0xbfb8aa3b, v42
	v_mul_f32_e32 v9, 0xbfb8aa3b, v43
	v_exp_f32_e32 v7, v7
	v_exp_f32_e32 v9, v9
	v_rcp_f32_e32 v10, v5
	v_mul_f32_e32 v11, 0xbfb8aa3b, v45
	v_add_f32_e32 v5, 1.0, v7
	v_add_f32_e32 v7, 1.0, v9
	v_mul_f32_e32 v9, 0xbfb8aa3b, v44
	v_exp_f32_e32 v9, v9
	v_exp_f32_e32 v11, v11
	v_rcp_f32_e32 v4, v4
	v_rcp_f32_e32 v5, v5
	v_rcp_f32_e32 v7, v7
	v_add_f32_e32 v9, 1.0, v9
	v_rcp_f32_e32 v9, v9
	v_add_f32_e32 v11, 1.0, v11
	v_rcp_f32_e32 v11, v11
	v_pk_fma_f32 v[4:5], v[4:5], s[30:31], 0.5 op_sel_hi:[1,0,0]
	s_andn2_b64 vcc, exec, s[44:45]
	v_cvt_u32_f32_e32 v12, v5
	v_cvt_u32_f32_e32 v13, v4
	v_pk_fma_f32 v[4:5], v[6:7], s[30:31], 0.5 op_sel_hi:[1,0,0]
	s_mov_b64 s[44:45], -1
	v_cvt_u32_f32_e32 v6, v4
	v_cvt_u32_f32_e32 v7, v5
	v_pk_fma_f32 v[4:5], v[8:9], s[30:31], 0.5 op_sel_hi:[1,0,0]
	v_lshlrev_b32_e32 v6, 8, v6
	v_cvt_u32_f32_sdwa v8, v4 dst_sel:WORD_1 dst_unused:UNUSED_PAD src0_sel:DWORD
	v_cvt_u32_f32_sdwa v9, v5 dst_sel:WORD_1 dst_unused:UNUSED_PAD src0_sel:DWORD
	v_pk_fma_f32 v[4:5], v[10:11], s[30:31], 0.5 op_sel_hi:[1,0,0]
	v_lshlrev_b32_e32 v7, 8, v7
	v_cvt_u32_f32_sdwa v4, v4 dst_sel:BYTE_3 dst_unused:UNUSED_PAD src0_sel:DWORD
	v_cvt_u32_f32_sdwa v5, v5 dst_sel:BYTE_3 dst_unused:UNUSED_PAD src0_sel:DWORD
	v_or_b32_e32 v6, v6, v13
	v_or_b32_e32 v7, v7, v12
	v_or_b32_e32 v6, v6, v8
	v_or_b32_e32 v7, v7, v9
	v_or_b32_e32 v4, v6, v4
	v_mul_f32_e32 v6, 0xbfb8aa3b, v38
	v_or_b32_e32 v5, v7, v5
	v_exp_f32_e32 v6, v6
	v_mul_f32_e32 v7, 0xbfb8aa3b, v39
	v_exp_f32_e32 v7, v7
	global_store_dwordx2 v[2:3], v[4:5], off
	v_add_f32_e32 v4, 1.0, v6
	v_mul_f32_e32 v6, 0xbfb8aa3b, v40
	v_add_f32_e32 v5, 1.0, v7
	v_exp_f32_e32 v7, v6
	v_mul_f32_e32 v6, 0xbfb8aa3b, v41
	v_exp_f32_e32 v9, v6
	v_rcp_f32_e32 v6, v5
	v_add_f32_e32 v5, 1.0, v7
	v_rcp_f32_e32 v8, v5
	v_add_f32_e32 v5, 1.0, v9
	v_mul_f32_e32 v7, 0xbfb8aa3b, v34
	v_mul_f32_e32 v9, 0xbfb8aa3b, v35
	v_exp_f32_e32 v7, v7
	v_exp_f32_e32 v9, v9
	v_rcp_f32_e32 v10, v5
	v_mul_f32_e32 v11, 0xbfb8aa3b, v37
	v_add_f32_e32 v5, 1.0, v7
	v_add_f32_e32 v7, 1.0, v9
	v_mul_f32_e32 v9, 0xbfb8aa3b, v36
	v_exp_f32_e32 v9, v9
	v_exp_f32_e32 v11, v11
	v_rcp_f32_e32 v4, v4
	v_rcp_f32_e32 v5, v5
	v_rcp_f32_e32 v7, v7
	v_add_f32_e32 v9, 1.0, v9
	v_rcp_f32_e32 v9, v9
	v_add_f32_e32 v11, 1.0, v11
	v_rcp_f32_e32 v11, v11
	v_pk_fma_f32 v[4:5], v[4:5], s[30:31], 0.5 op_sel_hi:[1,0,0]
	s_nop 0
	v_cvt_u32_f32_e32 v12, v5
	v_cvt_u32_f32_e32 v13, v4
	v_pk_fma_f32 v[4:5], v[6:7], s[30:31], 0.5 op_sel_hi:[1,0,0]
	s_nop 0
	v_cvt_u32_f32_e32 v6, v4
	v_cvt_u32_f32_e32 v7, v5
	v_pk_fma_f32 v[4:5], v[8:9], s[30:31], 0.5 op_sel_hi:[1,0,0]
	v_lshlrev_b32_e32 v6, 8, v6
	v_cvt_u32_f32_sdwa v8, v4 dst_sel:WORD_1 dst_unused:UNUSED_PAD src0_sel:DWORD
	v_cvt_u32_f32_sdwa v9, v5 dst_sel:WORD_1 dst_unused:UNUSED_PAD src0_sel:DWORD
	v_pk_fma_f32 v[4:5], v[10:11], s[30:31], 0.5 op_sel_hi:[1,0,0]
	v_lshlrev_b32_e32 v7, 8, v7
	v_cvt_u32_f32_sdwa v4, v4 dst_sel:BYTE_3 dst_unused:UNUSED_PAD src0_sel:DWORD
	v_cvt_u32_f32_sdwa v5, v5 dst_sel:BYTE_3 dst_unused:UNUSED_PAD src0_sel:DWORD
	v_or_b32_e32 v7, v7, v12
	v_or_b32_e32 v6, v6, v13
	v_or_b32_e32 v7, v7, v9
	v_or_b32_e32 v6, v6, v8
	v_or_b32_e32 v5, v7, v5
	v_or_b32_e32 v4, v6, v4
	global_store_dwordx2 v[2:3], v[4:5], off offset:2048
	s_cbranch_vccnz .LBB0_394
	s_andn2_b64 vcc, exec, s[16:17]
	s_cbranch_vccnz .LBB0_393
	s_barrier
	s_branch .LBB0_393

.LBB0_1227:
	v_lshl_or_b32 v138, s44, 6, v135
	v_lshl_add_u32 v138, s14, 8, v138
	v_ashrrev_i32_e32 v139, 31, v138
	s_lshl_b32 s12, s12, 8
	v_lshlrev_b64 v[138:139], 10, v[138:139]
	s_ashr_i32 s13, s12, 31
	v_lshl_add_u64 v[138:139], v[138:139], 0, s[12:13]
	v_or3_b32 v138, s52, v1, v138
	v_bfe_u32 v254, v138, 5, 5
	v_bfe_u32 v255, v138, 10, 4
	v_and_b32_e32 v138, 0xffffc01f, v138
	v_lshl_or_b32 v138, v254, 9, v138
	v_lshl_or_b32 v138, v255, 5, v138
	v_lshl_add_u64 v[140:141], s[8:9], 0, v[138:139]
	v_lshl_add_u64 v[142:143], s[6:7], 0, v[138:139]
	v_or_b32_e32 v138, 0x800, v138
	v_lshl_add_u64 v[144:145], s[8:9], 0, v[138:139]
	v_lshl_add_u64 v[138:139], s[6:7], 0, v[138:139]
	s_movk_i32 s8, 0x4000
	global_load_dwordx2 v[200:201], v[140:141], off
	global_load_dwordx2 v[202:203], v[142:143], off
	global_load_dwordx2 v[196:197], v[144:145], off
	global_load_dwordx2 v[198:199], v[138:139], off
	v_add_co_u32_e32 v138, vcc, s8, v140
	s_nop 1
	v_addc_co_u32_e32 v139, vcc, 0, v141, vcc
	v_add_co_u32_e32 v144, vcc, s8, v142
	s_mov_b32 s8, 0x8000
	s_nop 0
	v_addc_co_u32_e32 v145, vcc, 0, v143, vcc
	global_load_dwordx2 v[192:193], v[138:139], off
	global_load_dwordx2 v[194:195], v[144:145], off
	global_load_dwordx2 v[190:191], v[144:145], off offset:2048
	global_load_dwordx2 v[188:189], v[138:139], off offset:2048
	v_add_co_u32_e32 v138, vcc, s8, v140
	s_nop 1
	v_addc_co_u32_e32 v139, vcc, 0, v141, vcc
	v_add_co_u32_e32 v144, vcc, s8, v142
	s_mov_b32 s8, 0xc000
	s_nop 0
	v_addc_co_u32_e32 v145, vcc, 0, v143, vcc
	global_load_dwordx2 v[184:185], v[138:139], off
	global_load_dwordx2 v[186:187], v[144:145], off
	global_load_dwordx2 v[182:183], v[144:145], off offset:2048
	global_load_dwordx2 v[180:181], v[138:139], off offset:2048
	v_add_co_u32_e32 v138, vcc, s8, v140
	s_nop 1
	v_addc_co_u32_e32 v139, vcc, 0, v141, vcc
	v_add_co_u32_e32 v144, vcc, s8, v142
	s_nop 1
	v_addc_co_u32_e32 v145, vcc, 0, v143, vcc
	global_load_dwordx2 v[174:175], v[138:139], off
	global_load_dwordx2 v[176:177], v[144:145], off
	global_load_dwordx2 v[172:173], v[144:145], off offset:2048
	global_load_dwordx2 v[170:171], v[138:139], off offset:2048
	s_mov_b32 s8, 0x20000
	v_add_co_u32_e32 v138, vcc, s8, v140
	s_nop 1
	v_addc_co_u32_e32 v139, vcc, 0, v141, vcc
	v_add_co_u32_e32 v144, vcc, s8, v142
	s_mov_b32 s8, 0x24000
	s_nop 0
	v_addc_co_u32_e32 v145, vcc, 0, v143, vcc
	global_load_dwordx2 v[166:167], v[138:139], off
	global_load_dwordx2 v[168:169], v[144:145], off
	global_load_dwordx2 v[164:165], v[144:145], off offset:2048
	global_load_dwordx2 v[162:163], v[138:139], off offset:2048
	v_add_co_u32_e32 v138, vcc, s8, v140
	s_nop 1
	v_addc_co_u32_e32 v139, vcc, 0, v141, vcc
	v_add_co_u32_e32 v144, vcc, s8, v142
	s_mov_b32 s8, 0x28000
	s_nop 0
	v_addc_co_u32_e32 v145, vcc, 0, v143, vcc
	global_load_dwordx2 v[158:159], v[138:139], off
	global_load_dwordx2 v[160:161], v[144:145], off
	global_load_dwordx2 v[156:157], v[144:145], off offset:2048
	global_load_dwordx2 v[154:155], v[138:139], off offset:2048
	v_add_co_u32_e32 v138, vcc, s8, v140
	s_nop 1
	v_addc_co_u32_e32 v139, vcc, 0, v141, vcc
	v_add_co_u32_e32 v144, vcc, s8, v142
	s_mov_b32 s8, 0x2c000
	s_nop 0
	v_addc_co_u32_e32 v145, vcc, 0, v143, vcc
	global_load_dwordx2 v[150:151], v[138:139], off
	global_load_dwordx2 v[152:153], v[144:145], off
	global_load_dwordx2 v[148:149], v[144:145], off offset:2048
	global_load_dwordx2 v[146:147], v[138:139], off offset:2048
	v_add_co_u32_e32 v138, vcc, s8, v140
	s_nop 1
	v_addc_co_u32_e32 v139, vcc, 0, v141, vcc
	v_add_co_u32_e32 v140, vcc, 0x2c000, v142
	s_nop 1
	v_addc_co_u32_e32 v141, vcc, 0, v143, vcc
	global_load_dwordx2 v[142:143], v[138:139], off
	global_load_dwordx2 v[144:145], v[140:141], off
	s_nop 0
	global_load_dwordx2 v[140:141], v[140:141], off offset:2048
	s_nop 0
	global_load_dwordx2 v[138:139], v[138:139], off offset:2048
	v_readlane_b32 s72, v252, 40
	s_andn2_b64 vcc, exec, s[10:11]
	v_readlane_b32 s73, v252, 41
	s_cbranch_vccnz .LBB0_1229
	s_barrier

.LBB0_1237:
	v_lshl_add_u32 v130, s8, 8, v207
	v_ashrrev_i32_e32 v131, 31, v130
	s_lshl_b32 s0, s0, 8
	v_lshlrev_b64 v[130:131], 10, v[130:131]
	s_ashr_i32 s1, s0, 31
	v_lshl_add_u64 v[138:139], v[130:131], 0, s[0:1]
	v_or3_b32 v138, s21, v1, v138
	v_bfe_u32 v254, v138, 5, 5
	v_bfe_u32 v255, v138, 10, 4
	v_and_b32_e32 v130, 0xffffc01f, v138
	v_lshl_or_b32 v130, v254, 9, v130
	v_lshl_or_b32 v130, v255, 5, v130
	v_mov_b32_e32 v131, v139
	v_lshl_add_u64 v[130:131], s[6:7], 0, v[130:131]
	v_add_co_u32_e32 v132, vcc, 0x4000, v130
	s_mov_b32 s0, 0x8000
	s_nop 0
	v_addc_co_u32_e32 v133, vcc, 0, v131, vcc
	global_load_dwordx2 v[140:141], v[130:131], off
	global_load_dwordx2 v[142:143], v[130:131], off offset:2048
	global_load_dwordx2 v[144:145], v[132:133], off
	global_load_dwordx2 v[146:147], v[132:133], off offset:2048
	v_add_co_u32_e32 v132, vcc, 0x8000, v130
	s_nop 1
	v_addc_co_u32_e32 v133, vcc, 0, v131, vcc
	v_add_co_u32_e32 v148, vcc, 0xc000, v130
	s_nop 1
	v_addc_co_u32_e32 v149, vcc, 0, v131, vcc
	global_load_dwordx2 v[150:151], v[132:133], off
	global_load_dwordx2 v[136:137], v[132:133], off offset:2048
	global_load_dwordx2 v[134:135], v[148:149], off
	s_nop 0
	global_load_dwordx2 v[132:133], v[148:149], off offset:2048
	s_waitcnt vmcnt(0)
	v_cvt_f32_ubyte1_e32 v148, v140
	v_cvt_f32_ubyte0_e32 v1, v140
	v_mul_f32_e32 v149, 0x3b808081, v148
	v_cvt_f32_ubyte2_e32 v148, v140
	v_cvt_f32_ubyte3_e32 v140, v140
	v_mul_f32_e32 v153, 0x3b808081, v140
	v_cvt_f32_ubyte0_e32 v140, v141
	v_mul_f32_e32 v152, 0x3b808081, v148
	v_mul_f32_e32 v148, 0x3b808081, v140
	v_cvt_f32_ubyte1_e32 v140, v141
	v_mul_f32_e32 v154, 0x3b808081, v140
	v_cvt_f32_ubyte2_e32 v140, v141
	v_mul_f32_e32 v1, 0x3b808081, v1
	v_mul_f32_e32 v155, 0x3b808081, v140
	v_cvt_f32_ubyte3_e32 v140, v141
	v_mul_f32_e32 v156, 0x3b808081, v140
	v_max_f32_e32 v140, 0x3b008081, v1
	v_max_f32_e32 v148, 0x3b008081, v148
	v_max_f32_e32 v141, 0x3b008081, v149
	v_max_f32_e32 v149, 0x3b008081, v154
	v_pk_mul_f32 v[66:67], v[66:67], v[140:141]
	v_pk_mul_f32 v[140:141], v[74:75], v[148:149]
	v_max_f32_e32 v74, 0x3b008081, v152
	v_max_f32_e32 v75, 0x3b008081, v153
	v_pk_mul_f32 v[68:69], v[68:69], v[74:75]
	v_max_f32_e32 v148, 0x3b008081, v155
	v_cvt_pk_bf16_f32 v75, v68, v69
	v_cvt_f32_ubyte1_e32 v68, v142
	v_max_f32_e32 v149, 0x3b008081, v156
	v_mul_f32_e32 v69, 0x3b808081, v68
	v_cvt_f32_ubyte2_e32 v68, v142
	v_pk_mul_f32 v[148:149], v[76:77], v[148:149]
	v_cvt_pk_bf16_f32 v74, v66, v67
	v_lshl_add_u64 v[66:67], v[138:139], 1, s[4:5]
	v_mul_f32_e32 v138, 0x3b808081, v68
	v_cvt_f32_ubyte3_e32 v68, v142
	v_cvt_pk_bf16_f32 v76, v140, v141
	v_cvt_pk_bf16_f32 v77, v148, v149
	v_mul_f32_e32 v139, 0x3b808081, v68
	v_cvt_f32_ubyte0_e32 v68, v143
	global_store_dwordx4 v[66:67], v[74:77], off
	v_cvt_f32_ubyte0_e32 v1, v142
	v_mul_f32_e32 v1, 0x3b808081, v1
	v_mul_f32_e32 v74, 0x3b808081, v68
	v_cvt_f32_ubyte1_e32 v68, v143
	v_mul_f32_e32 v75, 0x3b808081, v68
	v_cvt_f32_ubyte2_e32 v68, v143
	v_mul_f32_e32 v140, 0x3b808081, v68
	v_cvt_f32_ubyte3_e32 v68, v143
	v_mul_f32_e32 v141, 0x3b808081, v68
	v_max_f32_e32 v68, 0x3b008081, v1
	v_max_f32_e32 v74, 0x3b008081, v74
	v_max_f32_e32 v69, 0x3b008081, v69
	v_max_f32_e32 v75, 0x3b008081, v75
	v_pk_mul_f32 v[68:69], v[78:79], v[68:69]
	v_pk_mul_f32 v[76:77], v[86:87], v[74:75]
	v_max_f32_e32 v74, 0x3b008081, v138
	v_max_f32_e32 v75, 0x3b008081, v139
	v_max_f32_e32 v78, 0x3b008081, v140
	v_pk_mul_f32 v[80:81], v[80:81], v[74:75]
	v_max_f32_e32 v79, 0x3b008081, v141
	v_cvt_pk_bf16_f32 v74, v68, v69
	v_cvt_f32_ubyte1_e32 v68, v144
	v_pk_mul_f32 v[78:79], v[88:89], v[78:79]
	v_mul_f32_e32 v69, 0x3b808081, v68
	v_cvt_f32_ubyte2_e32 v68, v144
	v_cvt_pk_bf16_f32 v76, v76, v77
	v_cvt_pk_bf16_f32 v77, v78, v79
	v_mul_f32_e32 v78, 0x3b808081, v68
	v_cvt_f32_ubyte3_e32 v68, v144
	v_cvt_pk_bf16_f32 v75, v80, v81
	v_mul_f32_e32 v79, 0x3b808081, v68
	v_cvt_f32_ubyte0_e32 v68, v145
	global_store_dwordx4 v[66:67], v[74:77], off offset:256
	v_cvt_f32_ubyte0_e32 v1, v144
	v_mul_f32_e32 v1, 0x3b808081, v1
	v_mul_f32_e32 v74, 0x3b808081, v68
	v_cvt_f32_ubyte1_e32 v68, v145
	v_mul_f32_e32 v75, 0x3b808081, v68
	v_cvt_f32_ubyte2_e32 v68, v145
	v_mul_f32_e32 v80, 0x3b808081, v68
	v_cvt_f32_ubyte3_e32 v68, v145
	v_mul_f32_e32 v86, 0x3b808081, v68
	v_max_f32_e32 v68, 0x3b008081, v1
	v_max_f32_e32 v74, 0x3b008081, v74
	v_max_f32_e32 v69, 0x3b008081, v69
	v_max_f32_e32 v75, 0x3b008081, v75
	v_pk_mul_f32 v[68:69], v[90:91], v[68:69]
	v_pk_mul_f32 v[76:77], v[94:95], v[74:75]
	v_max_f32_e32 v74, 0x3b008081, v78
	v_max_f32_e32 v78, 0x3b008081, v80
	v_max_f32_e32 v75, 0x3b008081, v79
	v_max_f32_e32 v79, 0x3b008081, v86
	v_pk_mul_f32 v[80:81], v[92:93], v[74:75]
	v_pk_mul_f32 v[78:79], v[96:97], v[78:79]
	v_cvt_pk_bf16_f32 v74, v68, v69
	v_add_co_u32_e32 v68, vcc, s0, v66
	v_cvt_pk_bf16_f32 v75, v80, v81
	v_cvt_pk_bf16_f32 v76, v76, v77
	v_cvt_pk_bf16_f32 v77, v78, v79
	v_addc_co_u32_e32 v69, vcc, 0, v67, vcc
	global_store_dwordx4 v[68:69], v[74:77], off
	v_cvt_f32_ubyte0_e32 v1, v146
	v_mul_f32_e32 v1, 0x3b808081, v1
	v_cvt_f32_ubyte1_e32 v74, v146
	v_mul_f32_e32 v75, 0x3b808081, v74
	v_cvt_f32_ubyte2_e32 v74, v146
	v_mul_f32_e32 v78, 0x3b808081, v74
	v_cvt_f32_ubyte3_e32 v74, v146
	v_mul_f32_e32 v79, 0x3b808081, v74
	v_cvt_f32_ubyte0_e32 v74, v147
	v_mul_f32_e32 v76, 0x3b808081, v74
	v_cvt_f32_ubyte1_e32 v74, v147
	v_mul_f32_e32 v77, 0x3b808081, v74
	v_cvt_f32_ubyte2_e32 v74, v147
	v_mul_f32_e32 v80, 0x3b808081, v74
	v_cvt_f32_ubyte3_e32 v74, v147
	v_mul_f32_e32 v81, 0x3b808081, v74
	v_max_f32_e32 v74, 0x3b008081, v1
	v_max_f32_e32 v76, 0x3b008081, v76
	v_max_f32_e32 v75, 0x3b008081, v75
	v_max_f32_e32 v77, 0x3b008081, v77
	v_max_f32_e32 v78, 0x3b008081, v78
	v_max_f32_e32 v80, 0x3b008081, v80
	v_max_f32_e32 v79, 0x3b008081, v79
	v_max_f32_e32 v81, 0x3b008081, v81
	v_pk_mul_f32 v[74:75], v[98:99], v[74:75]
	v_pk_mul_f32 v[76:77], v[102:103], v[76:77]
	v_pk_mul_f32 v[78:79], v[100:101], v[78:79]
	v_pk_mul_f32 v[80:81], v[104:105], v[80:81]
	v_cvt_pk_bf16_f32 v74, v74, v75
	v_cvt_pk_bf16_f32 v75, v78, v79
	v_cvt_pk_bf16_f32 v76, v76, v77
	v_cvt_pk_bf16_f32 v77, v80, v81
	global_store_dwordx4 v[68:69], v[74:77], off offset:256
	v_cvt_f32_ubyte1_e32 v68, v150
	v_mul_f32_e32 v69, 0x3b808081, v68
	v_cvt_f32_ubyte2_e32 v68, v150
	v_mul_f32_e32 v78, 0x3b808081, v68
	v_cvt_f32_ubyte3_e32 v68, v150
	v_mul_f32_e32 v79, 0x3b808081, v68
	v_cvt_f32_ubyte0_e32 v68, v151
	v_mul_f32_e32 v74, 0x3b808081, v68
	v_cvt_f32_ubyte1_e32 v68, v151
	v_cvt_f32_ubyte0_e32 v1, v150
	v_mul_f32_e32 v75, 0x3b808081, v68
	v_cvt_f32_ubyte2_e32 v68, v151
	v_mul_f32_e32 v1, 0x3b808081, v1
	v_mul_f32_e32 v80, 0x3b808081, v68
	v_cvt_f32_ubyte3_e32 v68, v151
	v_mul_f32_e32 v86, 0x3b808081, v68
	v_max_f32_e32 v68, 0x3b008081, v1
	v_max_f32_e32 v74, 0x3b008081, v74
	v_max_f32_e32 v69, 0x3b008081, v69
	v_max_f32_e32 v75, 0x3b008081, v75
	v_pk_mul_f32 v[68:69], v[110:111], v[68:69]
	v_pk_mul_f32 v[76:77], v[118:119], v[74:75]
	v_max_f32_e32 v74, 0x3b008081, v78
	v_max_f32_e32 v78, 0x3b008081, v80
	v_max_f32_e32 v75, 0x3b008081, v79
	v_max_f32_e32 v79, 0x3b008081, v86
	s_mov_b32 s0, 0x10000
	v_pk_mul_f32 v[80:81], v[112:113], v[74:75]
	v_pk_mul_f32 v[78:79], v[120:121], v[78:79]
	v_cvt_pk_bf16_f32 v74, v68, v69
	v_add_co_u32_e32 v68, vcc, s0, v66
	v_cvt_pk_bf16_f32 v75, v80, v81
	v_cvt_pk_bf16_f32 v76, v76, v77
	v_cvt_pk_bf16_f32 v77, v78, v79
	v_addc_co_u32_e32 v69, vcc, 0, v67, vcc
	global_store_dwordx4 v[68:69], v[74:77], off
	v_cvt_f32_ubyte0_e32 v1, v136
	v_mul_f32_e32 v1, 0x3b808081, v1
	v_cvt_f32_ubyte1_e32 v74, v136
	v_mul_f32_e32 v75, 0x3b808081, v74
	v_cvt_f32_ubyte2_e32 v74, v136
	v_mul_f32_e32 v78, 0x3b808081, v74
	v_cvt_f32_ubyte3_e32 v74, v136
	v_mul_f32_e32 v79, 0x3b808081, v74
	v_cvt_f32_ubyte0_e32 v74, v137
	v_mul_f32_e32 v76, 0x3b808081, v74
	v_cvt_f32_ubyte1_e32 v74, v137
	v_mul_f32_e32 v77, 0x3b808081, v74
	v_cvt_f32_ubyte2_e32 v74, v137
	v_mul_f32_e32 v80, 0x3b808081, v74
	v_cvt_f32_ubyte3_e32 v74, v137
	v_mul_f32_e32 v81, 0x3b808081, v74
	v_max_f32_e32 v74, 0x3b008081, v1
	v_max_f32_e32 v76, 0x3b008081, v76
	v_max_f32_e32 v75, 0x3b008081, v75
	v_max_f32_e32 v77, 0x3b008081, v77
	v_max_f32_e32 v78, 0x3b008081, v78
	v_max_f32_e32 v80, 0x3b008081, v80
	v_max_f32_e32 v79, 0x3b008081, v79
	v_max_f32_e32 v81, 0x3b008081, v81
	v_pk_mul_f32 v[74:75], v[122:123], v[74:75]
	v_pk_mul_f32 v[76:77], v[126:127], v[76:77]
	v_pk_mul_f32 v[78:79], v[124:125], v[78:79]
	v_pk_mul_f32 v[80:81], v[128:129], v[80:81]
	v_cvt_pk_bf16_f32 v74, v74, v75
	v_cvt_pk_bf16_f32 v75, v78, v79
	v_cvt_pk_bf16_f32 v76, v76, v77
	v_cvt_pk_bf16_f32 v77, v80, v81
	global_store_dwordx4 v[68:69], v[74:77], off offset:256
	v_cvt_f32_ubyte1_e32 v68, v134
	v_mul_f32_e32 v69, 0x3b808081, v68
	v_cvt_f32_ubyte2_e32 v68, v134
	v_mul_f32_e32 v78, 0x3b808081, v68
	v_cvt_f32_ubyte3_e32 v68, v134
	v_mul_f32_e32 v79, 0x3b808081, v68
	v_cvt_f32_ubyte0_e32 v68, v135
	v_mul_f32_e32 v74, 0x3b808081, v68
	v_cvt_f32_ubyte1_e32 v68, v135
	v_mul_f32_e32 v75, 0x3b808081, v68
	v_cvt_f32_ubyte2_e32 v68, v135
	v_cvt_f32_ubyte0_e32 v1, v134
	v_mul_f32_e32 v80, 0x3b808081, v68
	v_cvt_f32_ubyte3_e32 v68, v135
	v_mul_f32_e32 v1, 0x3b808081, v1
	v_mul_f32_e32 v86, 0x3b808081, v68
	v_max_f32_e32 v74, 0x3b008081, v74
	v_max_f32_e32 v75, 0x3b008081, v75
	v_max_f32_e32 v68, 0x3b008081, v1
	v_max_f32_e32 v69, 0x3b008081, v69
	v_pk_mul_f32 v[76:77], v[106:107], v[74:75]
	v_max_f32_e32 v74, 0x3b008081, v78
	v_max_f32_e32 v78, 0x3b008081, v80
	v_max_f32_e32 v75, 0x3b008081, v79
	v_max_f32_e32 v79, 0x3b008081, v86
	v_pk_mul_f32 v[68:69], v[114:115], v[68:69]
	v_pk_mul_f32 v[78:79], v[108:109], v[78:79]
	s_mov_b32 s0, 0x18000
	v_pk_mul_f32 v[80:81], v[116:117], v[74:75]
	v_cvt_pk_bf16_f32 v74, v68, v69
	v_cvt_pk_bf16_f32 v76, v76, v77
	v_cvt_pk_bf16_f32 v77, v78, v79
	v_add_co_u32_e32 v78, vcc, s0, v66
	v_cvt_f32_ubyte1_e32 v68, v132
	v_cvt_pk_bf16_f32 v75, v80, v81
	v_addc_co_u32_e32 v79, vcc, 0, v67, vcc
	v_mul_f32_e32 v69, 0x3b808081, v68
	v_cvt_f32_ubyte2_e32 v68, v132
	global_store_dwordx4 v[78:79], v[74:77], off
	v_cvt_f32_ubyte0_e32 v1, v132
	v_mul_f32_e32 v1, 0x3b808081, v1
	v_mul_f32_e32 v76, 0x3b808081, v68
	v_cvt_f32_ubyte3_e32 v68, v132
	v_mul_f32_e32 v77, 0x3b808081, v68
	v_cvt_f32_ubyte0_e32 v68, v133
	v_mul_f32_e32 v74, 0x3b808081, v68
	v_cvt_f32_ubyte1_e32 v68, v133
	v_mul_f32_e32 v75, 0x3b808081, v68
	v_cvt_f32_ubyte2_e32 v68, v133
	v_mul_f32_e32 v80, 0x3b808081, v68
	v_cvt_f32_ubyte3_e32 v68, v133
	v_mul_f32_e32 v81, 0x3b808081, v68
	v_max_f32_e32 v74, 0x3b008081, v74
	v_max_f32_e32 v75, 0x3b008081, v75
	v_max_f32_e32 v68, 0x3b008081, v1
	v_max_f32_e32 v69, 0x3b008081, v69
	v_pk_mul_f32 v[70:71], v[70:71], v[74:75]
	v_max_f32_e32 v74, 0x3b008081, v76
	v_max_f32_e32 v76, 0x3b008081, v80
	v_max_f32_e32 v75, 0x3b008081, v77
	v_max_f32_e32 v77, 0x3b008081, v81
	v_pk_mul_f32 v[68:69], v[82:83], v[68:69]
	v_pk_mul_f32 v[74:75], v[84:85], v[74:75]
	v_pk_mul_f32 v[72:73], v[72:73], v[76:77]
	v_cvt_pk_bf16_f32 v68, v68, v69
	v_cvt_pk_bf16_f32 v69, v74, v75
	v_cvt_pk_bf16_f32 v70, v70, v71
	v_cvt_pk_bf16_f32 v71, v72, v73
	global_store_dwordx4 v[78:79], v[68:71], off offset:256
	s_mov_b32 s0, 0x20000
	s_nop 0
	v_add_co_u32_e32 v68, vcc, s0, v130
	s_mov_b32 s0, 0x24000
	s_nop 0
	v_addc_co_u32_e32 v69, vcc, 0, v131, vcc
	v_add_co_u32_e32 v70, vcc, s0, v130
	s_mov_b32 s0, 0x28000
	s_nop 0
	v_addc_co_u32_e32 v71, vcc, 0, v131, vcc
	v_add_co_u32_e32 v82, vcc, s0, v130
	s_mov_b32 s0, 0x2c000
	s_nop 0
	v_addc_co_u32_e32 v83, vcc, 0, v131, vcc
	v_add_co_u32_e32 v84, vcc, s0, v130
	global_load_dwordx2 v[74:75], v[68:69], off
	global_load_dwordx2 v[76:77], v[68:69], off offset:2048
	global_load_dwordx2 v[78:79], v[70:71], off
	global_load_dwordx2 v[80:81], v[70:71], off offset:2048
	v_addc_co_u32_e32 v85, vcc, 0, v131, vcc
	global_load_dwordx2 v[86:87], v[82:83], off
	global_load_dwordx2 v[72:73], v[82:83], off offset:2048
	global_load_dwordx2 v[70:71], v[84:85], off
	global_load_dwordx2 v[68:69], v[84:85], off offset:2048
	s_waitcnt vmcnt(7)
	v_cvt_f32_ubyte1_e32 v82, v74
	v_cvt_f32_ubyte0_e32 v1, v74
	v_mul_f32_e32 v83, 0x3b808081, v82
	v_cvt_f32_ubyte2_e32 v82, v74
	v_cvt_f32_ubyte3_e32 v74, v74
	v_mul_f32_e32 v85, 0x3b808081, v74
	v_cvt_f32_ubyte0_e32 v74, v75
	v_mul_f32_e32 v84, 0x3b808081, v82
	v_mul_f32_e32 v82, 0x3b808081, v74
	v_cvt_f32_ubyte1_e32 v74, v75
	v_mul_f32_e32 v88, 0x3b808081, v74
	v_cvt_f32_ubyte2_e32 v74, v75
	v_mul_f32_e32 v1, 0x3b808081, v1
	v_mul_f32_e32 v89, 0x3b808081, v74
	v_cvt_f32_ubyte3_e32 v74, v75
	v_mul_f32_e32 v90, 0x3b808081, v74
	v_max_f32_e32 v74, 0x3b008081, v1
	v_max_f32_e32 v82, 0x3b008081, v82
	v_max_f32_e32 v75, 0x3b008081, v83
	v_max_f32_e32 v83, 0x3b008081, v88
	v_pk_mul_f32 v[62:63], v[62:63], v[74:75]
	v_pk_mul_f32 v[74:75], v[58:59], v[82:83]
	v_max_f32_e32 v58, 0x3b008081, v84
	v_max_f32_e32 v82, 0x3b008081, v89
	v_max_f32_e32 v59, 0x3b008081, v85
	v_max_f32_e32 v83, 0x3b008081, v90
	s_mov_b32 s0, 0x40000
	v_pk_mul_f32 v[64:65], v[64:65], v[58:59]
	v_pk_mul_f32 v[82:83], v[60:61], v[82:83]
	v_cvt_pk_bf16_f32 v58, v62, v63
	v_add_co_u32_e32 v62, vcc, s0, v66
	v_cvt_pk_bf16_f32 v59, v64, v65
	v_cvt_pk_bf16_f32 v60, v74, v75
	v_cvt_pk_bf16_f32 v61, v82, v83
	v_addc_co_u32_e32 v63, vcc, 0, v67, vcc
	global_store_dwordx4 v[62:63], v[58:61], off
	s_waitcnt vmcnt(7)
	v_cvt_f32_ubyte0_e32 v1, v76
	v_mul_f32_e32 v1, 0x3b808081, v1
	v_cvt_f32_ubyte1_e32 v58, v76
	v_mul_f32_e32 v59, 0x3b808081, v58
	v_cvt_f32_ubyte2_e32 v58, v76
	v_mul_f32_e32 v64, 0x3b808081, v58
	v_cvt_f32_ubyte3_e32 v58, v76
	v_mul_f32_e32 v65, 0x3b808081, v58
	v_cvt_f32_ubyte0_e32 v58, v77
	v_mul_f32_e32 v60, 0x3b808081, v58
	v_cvt_f32_ubyte1_e32 v58, v77
	v_mul_f32_e32 v61, 0x3b808081, v58
	v_cvt_f32_ubyte2_e32 v58, v77
	v_mul_f32_e32 v74, 0x3b808081, v58
	v_cvt_f32_ubyte3_e32 v58, v77
	v_mul_f32_e32 v75, 0x3b808081, v58
	v_max_f32_e32 v58, 0x3b008081, v1
	v_max_f32_e32 v60, 0x3b008081, v60
	v_max_f32_e32 v59, 0x3b008081, v59
	v_max_f32_e32 v61, 0x3b008081, v61
	v_pk_mul_f32 v[54:55], v[54:55], v[58:59]
	v_pk_mul_f32 v[58:59], v[50:51], v[60:61]
	v_max_f32_e32 v50, 0x3b008081, v64
	v_max_f32_e32 v60, 0x3b008081, v74
	v_max_f32_e32 v51, 0x3b008081, v65
	v_max_f32_e32 v61, 0x3b008081, v75
	v_pk_mul_f32 v[56:57], v[56:57], v[50:51]
	v_pk_mul_f32 v[60:61], v[52:53], v[60:61]
	v_cvt_pk_bf16_f32 v50, v54, v55
	v_cvt_pk_bf16_f32 v51, v56, v57
	v_cvt_pk_bf16_f32 v52, v58, v59
	v_cvt_pk_bf16_f32 v53, v60, v61
	global_store_dwordx4 v[62:63], v[50:53], off offset:256
	s_waitcnt vmcnt(7)
	v_cvt_f32_ubyte0_e32 v1, v78
	v_mul_f32_e32 v1, 0x3b808081, v1
	v_cvt_f32_ubyte1_e32 v50, v78
	v_mul_f32_e32 v51, 0x3b808081, v50
	v_cvt_f32_ubyte2_e32 v50, v78
	v_mul_f32_e32 v54, 0x3b808081, v50
	v_cvt_f32_ubyte3_e32 v50, v78
	v_mul_f32_e32 v55, 0x3b808081, v50
	v_cvt_f32_ubyte0_e32 v50, v79
	v_mul_f32_e32 v52, 0x3b808081, v50
	v_cvt_f32_ubyte1_e32 v50, v79
	v_mul_f32_e32 v53, 0x3b808081, v50
	v_cvt_f32_ubyte2_e32 v50, v79
	v_mul_f32_e32 v56, 0x3b808081, v50
	v_cvt_f32_ubyte3_e32 v50, v79
	v_mul_f32_e32 v57, 0x3b808081, v50
	v_max_f32_e32 v50, 0x3b008081, v1
	v_max_f32_e32 v52, 0x3b008081, v52
	v_max_f32_e32 v51, 0x3b008081, v51
	v_max_f32_e32 v53, 0x3b008081, v53
	v_pk_mul_f32 v[46:47], v[46:47], v[50:51]
	v_pk_mul_f32 v[50:51], v[42:43], v[52:53]
	v_max_f32_e32 v42, 0x3b008081, v54
	v_max_f32_e32 v52, 0x3b008081, v56
	v_max_f32_e32 v43, 0x3b008081, v55
	v_max_f32_e32 v53, 0x3b008081, v57
	s_mov_b32 s0, 0x48000
	v_pk_mul_f32 v[48:49], v[48:49], v[42:43]
	v_pk_mul_f32 v[52:53], v[44:45], v[52:53]
	v_cvt_pk_bf16_f32 v42, v46, v47
	v_add_co_u32_e32 v46, vcc, s0, v66
	v_cvt_pk_bf16_f32 v43, v48, v49
	v_cvt_pk_bf16_f32 v44, v50, v51
	v_cvt_pk_bf16_f32 v45, v52, v53
	v_addc_co_u32_e32 v47, vcc, 0, v67, vcc
	global_store_dwordx4 v[46:47], v[42:45], off
	s_waitcnt vmcnt(7)
	v_cvt_f32_ubyte0_e32 v1, v80
	v_mul_f32_e32 v1, 0x3b808081, v1
	v_cvt_f32_ubyte1_e32 v42, v80
	v_mul_f32_e32 v43, 0x3b808081, v42
	v_cvt_f32_ubyte2_e32 v42, v80
	v_mul_f32_e32 v48, 0x3b808081, v42
	v_cvt_f32_ubyte3_e32 v42, v80
	v_mul_f32_e32 v49, 0x3b808081, v42
	v_cvt_f32_ubyte0_e32 v42, v81
	v_mul_f32_e32 v44, 0x3b808081, v42
	v_cvt_f32_ubyte1_e32 v42, v81
	v_mul_f32_e32 v45, 0x3b808081, v42
	v_cvt_f32_ubyte2_e32 v42, v81
	v_mul_f32_e32 v50, 0x3b808081, v42
	v_cvt_f32_ubyte3_e32 v42, v81
	v_mul_f32_e32 v51, 0x3b808081, v42
	v_max_f32_e32 v42, 0x3b008081, v1
	v_max_f32_e32 v44, 0x3b008081, v44
	v_max_f32_e32 v43, 0x3b008081, v43
	v_max_f32_e32 v45, 0x3b008081, v45
	v_pk_mul_f32 v[38:39], v[38:39], v[42:43]
	v_pk_mul_f32 v[42:43], v[34:35], v[44:45]
	v_max_f32_e32 v34, 0x3b008081, v48
	v_max_f32_e32 v44, 0x3b008081, v50
	v_max_f32_e32 v35, 0x3b008081, v49
	v_max_f32_e32 v45, 0x3b008081, v51
	v_pk_mul_f32 v[40:41], v[40:41], v[34:35]
	v_pk_mul_f32 v[44:45], v[36:37], v[44:45]
	v_cvt_pk_bf16_f32 v34, v38, v39
	v_cvt_pk_bf16_f32 v35, v40, v41
	v_cvt_pk_bf16_f32 v36, v42, v43
	v_cvt_pk_bf16_f32 v37, v44, v45
	global_store_dwordx4 v[46:47], v[34:37], off offset:256
	s_waitcnt vmcnt(7)
	v_cvt_f32_ubyte0_e32 v1, v86
	v_mul_f32_e32 v1, 0x3b808081, v1
	v_cvt_f32_ubyte1_e32 v34, v86
	v_mul_f32_e32 v35, 0x3b808081, v34
	v_cvt_f32_ubyte2_e32 v34, v86
	v_mul_f32_e32 v38, 0x3b808081, v34
	v_cvt_f32_ubyte3_e32 v34, v86
	v_mul_f32_e32 v39, 0x3b808081, v34
	v_cvt_f32_ubyte0_e32 v34, v87
	v_mul_f32_e32 v36, 0x3b808081, v34
	v_cvt_f32_ubyte1_e32 v34, v87
	v_mul_f32_e32 v37, 0x3b808081, v34
	v_cvt_f32_ubyte2_e32 v34, v87
	v_mul_f32_e32 v40, 0x3b808081, v34
	v_cvt_f32_ubyte3_e32 v34, v87
	v_mul_f32_e32 v41, 0x3b808081, v34
	v_max_f32_e32 v34, 0x3b008081, v1
	v_max_f32_e32 v36, 0x3b008081, v36
	v_max_f32_e32 v35, 0x3b008081, v35
	v_max_f32_e32 v37, 0x3b008081, v37
	v_pk_mul_f32 v[26:27], v[26:27], v[34:35]
	v_pk_mul_f32 v[34:35], v[18:19], v[36:37]
	v_max_f32_e32 v18, 0x3b008081, v38
	v_max_f32_e32 v36, 0x3b008081, v40
	v_max_f32_e32 v19, 0x3b008081, v39
	v_max_f32_e32 v37, 0x3b008081, v41
	s_mov_b32 s0, 0x50000
	v_pk_mul_f32 v[28:29], v[28:29], v[18:19]
	v_pk_mul_f32 v[36:37], v[20:21], v[36:37]
	v_cvt_pk_bf16_f32 v18, v26, v27
	v_add_co_u32_e32 v26, vcc, s0, v66
	v_cvt_pk_bf16_f32 v19, v28, v29
	v_cvt_pk_bf16_f32 v20, v34, v35
	v_cvt_pk_bf16_f32 v21, v36, v37
	v_addc_co_u32_e32 v27, vcc, 0, v67, vcc
	global_store_dwordx4 v[26:27], v[18:21], off
	s_waitcnt vmcnt(7)
	v_cvt_f32_ubyte0_e32 v1, v72
	v_mul_f32_e32 v1, 0x3b808081, v1
	v_cvt_f32_ubyte1_e32 v18, v72
	v_mul_f32_e32 v19, 0x3b808081, v18
	v_cvt_f32_ubyte2_e32 v18, v72
	v_mul_f32_e32 v28, 0x3b808081, v18
	v_cvt_f32_ubyte3_e32 v18, v72
	v_mul_f32_e32 v29, 0x3b808081, v18
	v_cvt_f32_ubyte0_e32 v18, v73
	v_mul_f32_e32 v20, 0x3b808081, v18
	v_cvt_f32_ubyte1_e32 v18, v73
	v_mul_f32_e32 v21, 0x3b808081, v18
	v_cvt_f32_ubyte2_e32 v18, v73
	v_mul_f32_e32 v34, 0x3b808081, v18
	v_cvt_f32_ubyte3_e32 v18, v73
	v_mul_f32_e32 v35, 0x3b808081, v18
	v_max_f32_e32 v20, 0x3b008081, v20
	v_max_f32_e32 v21, 0x3b008081, v21
	v_max_f32_e32 v18, 0x3b008081, v1
	v_max_f32_e32 v19, 0x3b008081, v19
	v_pk_mul_f32 v[20:21], v[22:23], v[20:21]
	v_max_f32_e32 v22, 0x3b008081, v28
	v_max_f32_e32 v28, 0x3b008081, v34
	v_max_f32_e32 v23, 0x3b008081, v29
	v_max_f32_e32 v29, 0x3b008081, v35
	v_pk_mul_f32 v[18:19], v[30:31], v[18:19]
	v_pk_mul_f32 v[22:23], v[32:33], v[22:23]
	v_pk_mul_f32 v[24:25], v[24:25], v[28:29]
	v_cvt_pk_bf16_f32 v18, v18, v19
	v_cvt_pk_bf16_f32 v19, v22, v23
	v_cvt_pk_bf16_f32 v20, v20, v21
	v_cvt_pk_bf16_f32 v21, v24, v25
	global_store_dwordx4 v[26:27], v[18:21], off offset:256
	s_waitcnt vmcnt(7)
	v_cvt_f32_ubyte0_e32 v1, v70
	v_mul_f32_e32 v1, 0x3b808081, v1
	v_cvt_f32_ubyte1_e32 v18, v70
	v_mul_f32_e32 v19, 0x3b808081, v18
	v_cvt_f32_ubyte2_e32 v18, v70
	v_mul_f32_e32 v22, 0x3b808081, v18
	v_cvt_f32_ubyte3_e32 v18, v70
	v_mul_f32_e32 v23, 0x3b808081, v18
	v_cvt_f32_ubyte0_e32 v18, v71
	v_mul_f32_e32 v20, 0x3b808081, v18
	v_cvt_f32_ubyte1_e32 v18, v71
	v_mul_f32_e32 v21, 0x3b808081, v18
	v_cvt_f32_ubyte2_e32 v18, v71
	v_mul_f32_e32 v24, 0x3b808081, v18
	v_cvt_f32_ubyte3_e32 v18, v71
	v_mul_f32_e32 v25, 0x3b808081, v18
	v_max_f32_e32 v18, 0x3b008081, v1
	v_max_f32_e32 v20, 0x3b008081, v20
	v_max_f32_e32 v19, 0x3b008081, v19
	v_max_f32_e32 v21, 0x3b008081, v21
	v_pk_mul_f32 v[10:11], v[10:11], v[18:19]
	v_pk_mul_f32 v[18:19], v[2:3], v[20:21]
	v_max_f32_e32 v2, 0x3b008081, v22
	v_max_f32_e32 v20, 0x3b008081, v24
	v_max_f32_e32 v3, 0x3b008081, v23
	v_max_f32_e32 v21, 0x3b008081, v25
	s_mov_b32 s0, 0x58000
	v_pk_mul_f32 v[12:13], v[12:13], v[2:3]
	v_pk_mul_f32 v[20:21], v[4:5], v[20:21]
	v_cvt_pk_bf16_f32 v2, v10, v11
	v_add_co_u32_e32 v10, vcc, s0, v66
	v_cvt_pk_bf16_f32 v3, v12, v13
	v_cvt_pk_bf16_f32 v4, v18, v19
	v_cvt_pk_bf16_f32 v5, v20, v21
	v_addc_co_u32_e32 v11, vcc, 0, v67, vcc
	global_store_dwordx4 v[10:11], v[2:5], off
	s_waitcnt vmcnt(7)
	v_cvt_f32_ubyte0_e32 v1, v68
	v_mul_f32_e32 v1, 0x3b808081, v1
	v_cvt_f32_ubyte1_e32 v2, v68
	v_mul_f32_e32 v3, 0x3b808081, v2
	v_cvt_f32_ubyte2_e32 v2, v68
	v_mul_f32_e32 v12, 0x3b808081, v2
	v_cvt_f32_ubyte3_e32 v2, v68
	v_mul_f32_e32 v13, 0x3b808081, v2
	v_cvt_f32_ubyte0_e32 v2, v69
	v_mul_f32_e32 v4, 0x3b808081, v2
	v_cvt_f32_ubyte1_e32 v2, v69
	v_mul_f32_e32 v5, 0x3b808081, v2
	v_cvt_f32_ubyte2_e32 v2, v69
	v_mul_f32_e32 v18, 0x3b808081, v2
	v_cvt_f32_ubyte3_e32 v2, v69
	v_mul_f32_e32 v19, 0x3b808081, v2
	v_max_f32_e32 v4, 0x3b008081, v4
	v_max_f32_e32 v5, 0x3b008081, v5
	v_max_f32_e32 v2, 0x3b008081, v1
	v_max_f32_e32 v3, 0x3b008081, v3
	v_pk_mul_f32 v[4:5], v[6:7], v[4:5]
	v_max_f32_e32 v6, 0x3b008081, v12
	v_max_f32_e32 v12, 0x3b008081, v18
	v_max_f32_e32 v7, 0x3b008081, v13
	v_max_f32_e32 v13, 0x3b008081, v19
	v_pk_mul_f32 v[2:3], v[14:15], v[2:3]
	v_pk_mul_f32 v[6:7], v[16:17], v[6:7]
	v_pk_mul_f32 v[8:9], v[8:9], v[12:13]
	v_cvt_pk_bf16_f32 v2, v2, v3
	v_cvt_pk_bf16_f32 v3, v6, v7
	v_cvt_pk_bf16_f32 v4, v4, v5
	v_cvt_pk_bf16_f32 v5, v8, v9
	global_store_dwordx4 v[10:11], v[2:5], off offset:256
	s_waitcnt vmcnt(0)
	s_barrier
